# row-scale (ss) blocks of in-proj0, in-proj1 and FFN-up tiles staged into spare LDS by DMA during the K-loop; epilogues read them with ds_read
# speedup vs baseline: 1.0052x; 1.0052x over previous
.LBB0_79:
	s_and_b64 s[6:7], s[6:7], exec
	v_readlane_b32 s6, v254, 37
	v_readlane_b32 s22, v254, 39
	v_bfe_u32 v20, v16, 4, 2
	v_readlane_b32 s7, v254, 38
	v_readlane_b32 s23, v254, 40
	v_and_b32_e32 v17, 15, v16
	v_lshlrev_b32_e32 v18, 4, v20
	v_lshlrev_b32_e32 v16, 2, v16
	s_cselect_b32 s7, s7, s23
	s_cselect_b32 s6, s6, s22
	v_lshl_or_b32 v199, s21, 6, v17
	v_lshl_or_b32 v17, v17, 6, v18
	s_lshl_b32 s1, s21, 13
	v_and_b32_e32 v16, 32, v16
	v_bitop3_b32 v21, v17, s1, v16 bitop3:0xde
	s_lshl_b32 s1, s20, 5
	s_and_b32 s1, s1, 0x60
	s_lshl_b32 s20, s1, 7
	s_add_i32 m0, s46, 0x18000
	v_lshl_add_u64 v[8:9], v[8:9], 0, s[12:13]
	v_bitop3_b32 v201, v17, s20, v16 bitop3:0xde
	s_waitcnt vmcnt(2)
	s_barrier
	global_load_lds_dwordx4 v[8:9], off
	v_lshl_add_u64 v[6:7], v[6:7], 0, s[12:13]
	s_add_i32 m0, s46, 0x1a000
	s_add_i32 s20, s46, 0x8000
	s_add_i32 s21, s46, 0xa000
	global_load_lds_dwordx4 v[6:7], off
	v_lshl_add_u64 v[4:5], v[4:5], 0, s[12:13]
	s_mov_b32 m0, s20
	s_add_u32 s22, s30, 0x40080
	global_load_lds_dwordx4 v[4:5], off
	v_lshl_add_u64 v[2:3], v[2:3], 0, s[12:13]
	s_mov_b32 m0, s21
	s_addc_u32 s23, s31, 0
	global_load_lds_dwordx4 v[2:3], off
	s_add_i32 m0, s46, 0x1c000
	v_lshl_add_u64 v[2:3], s[22:23], 0, v[0:1]
	global_load_lds_dwordx4 v[2:3], off
	v_lshl_add_u64 v[2:3], s[22:23], 0, v[154:155]
	s_add_i32 m0, s46, 0x1e000
	v_mov_b32_e32 v19, v1
	global_load_lds_dwordx4 v[2:3], off
	v_lshlrev_b32_e32 v2, 14, v14
	v_and_b32_e32 v2, 0xffff8000, v2
	v_lshl_add_u32 v2, v13, 11, v2
	v_and_b32_e32 v3, 1, v14
	v_lshl_or_b32 v2, v3, 6, v2
	v_lshl_add_u32 v178, v15, 1, v2
	v_lshlrev_b32_e32 v2, 14, v10
	v_and_b32_e32 v2, 0xffff8000, v2
	s_waitcnt vmcnt(6)
	v_lshl_add_u32 v2, v11, 11, v2
	v_and_b32_e32 v3, 1, v10
	s_mov_b64 s[100:101], s[6:7]
	v_lshl_add_u64 v[160:161], s[6:7], 0, v[18:19]
	v_lshl_or_b32 v2, v3, 6, v2
	v_readlane_b32 s6, v253, 4
	v_lshl_or_b32 v204, v20, 3, s1
	v_mov_b32_e32 v179, v1
	v_lshl_add_u32 v180, v12, 1, v2
	v_mov_b32_e32 v181, v1
	s_mov_b32 s54, 0
	v_add_u32_e32 v205, 0, v21
	v_readlane_b32 s34, v253, 0
	s_mov_b32 s55, s6
	s_barrier
	v_readlane_b32 s7, v253, 5

.LBB0_82:
	s_ashr_i32 s27, s26, 31
	v_mov_b64_e32 v[2:3], 0xb00
	s_lshl_b64 s[22:23], s[26:27], 19
	v_cmp_lt_i64_e32 vcc, s[36:37], v[2:3]
	s_add_u32 s36, s96, s22
	s_addc_u32 s37, s97, s23
	s_and_b64 s[22:23], vcc, exec
	s_cselect_b32 s27, s37, s29
	s_cselect_b32 s56, s36, s28
	s_ashr_i32 s7, s6, 31
	s_lshl_b64 s[22:23], s[6:7], 19
	s_add_u32 s44, s4, s22
	s_addc_u32 s45, s16, s23
	s_and_b64 s[22:23], vcc, exec
	s_cselect_b32 s7, s45, s31
	s_cselect_b32 s57, s44, s30
	s_add_u32 s28, s28, 0x40080
	s_addc_u32 s29, s29, 0
	s_add_u32 s58, s30, 0x100
	v_mov_b32_e32 v2, 0
	s_addc_u32 s59, s31, 0
	s_mov_b32 s60, -2
	v_mov_b32_e32 v3, v2
	v_mov_b32_e32 v4, v2
	v_mov_b32_e32 v5, v2
	v_mov_b32_e32 v10, v2
	v_mov_b32_e32 v11, v2
	v_mov_b32_e32 v12, v2
	v_mov_b32_e32 v13, v2
	v_mov_b32_e32 v18, v2
	v_mov_b32_e32 v19, v2
	v_mov_b32_e32 v20, v2
	v_mov_b32_e32 v21, v2
	v_mov_b32_e32 v26, v2
	v_mov_b32_e32 v27, v2
	v_mov_b32_e32 v28, v2
	v_mov_b32_e32 v29, v2
	v_mov_b32_e32 v34, v2
	v_mov_b32_e32 v35, v2
	v_mov_b32_e32 v36, v2
	v_mov_b32_e32 v37, v2
	v_mov_b32_e32 v42, v2
	v_mov_b32_e32 v43, v2
	v_mov_b32_e32 v44, v2
	v_mov_b32_e32 v45, v2
	v_mov_b32_e32 v50, v2
	v_mov_b32_e32 v51, v2
	v_mov_b32_e32 v52, v2
	v_mov_b32_e32 v53, v2
	v_mov_b32_e32 v58, v2
	v_mov_b32_e32 v59, v2
	v_mov_b32_e32 v60, v2
	v_mov_b32_e32 v61, v2
	v_mov_b32_e32 v6, v2
	v_mov_b32_e32 v7, v2
	v_mov_b32_e32 v8, v2
	v_mov_b32_e32 v9, v2
	v_mov_b32_e32 v14, v2
	v_mov_b32_e32 v15, v2
	v_mov_b32_e32 v16, v2
	v_mov_b32_e32 v17, v2
	v_mov_b32_e32 v22, v2
	v_mov_b32_e32 v23, v2
	v_mov_b32_e32 v24, v2
	v_mov_b32_e32 v25, v2
	v_mov_b32_e32 v30, v2
	v_mov_b32_e32 v31, v2
	v_mov_b32_e32 v32, v2
	v_mov_b32_e32 v33, v2
	v_mov_b32_e32 v38, v2
	v_mov_b32_e32 v39, v2
	v_mov_b32_e32 v40, v2
	v_mov_b32_e32 v41, v2
	v_mov_b32_e32 v46, v2
	v_mov_b32_e32 v47, v2
	v_mov_b32_e32 v48, v2
	v_mov_b32_e32 v49, v2
	v_mov_b32_e32 v54, v2
	v_mov_b32_e32 v55, v2
	v_mov_b32_e32 v56, v2
	v_mov_b32_e32 v57, v2
	v_mov_b32_e32 v62, v2
	v_mov_b32_e32 v63, v2
	v_mov_b32_e32 v64, v2
	v_mov_b32_e32 v65, v2
	v_mov_b32_e32 v66, v2
	v_mov_b32_e32 v67, v2
	v_mov_b32_e32 v68, v2
	v_mov_b32_e32 v69, v2
	v_mov_b32_e32 v74, v2
	v_mov_b32_e32 v75, v2
	v_mov_b32_e32 v76, v2
	v_mov_b32_e32 v77, v2
	v_mov_b32_e32 v82, v2
	v_mov_b32_e32 v83, v2
	v_mov_b32_e32 v84, v2
	v_mov_b32_e32 v85, v2
	v_mov_b32_e32 v90, v2
	v_mov_b32_e32 v91, v2
	v_mov_b32_e32 v92, v2
	v_mov_b32_e32 v93, v2
	v_mov_b32_e32 v98, v2
	v_mov_b32_e32 v99, v2
	v_mov_b32_e32 v100, v2
	v_mov_b32_e32 v101, v2
	v_mov_b32_e32 v106, v2
	v_mov_b32_e32 v107, v2
	v_mov_b32_e32 v108, v2
	v_mov_b32_e32 v109, v2
	v_mov_b32_e32 v114, v2
	v_mov_b32_e32 v115, v2
	v_mov_b32_e32 v116, v2
	v_mov_b32_e32 v117, v2
	v_mov_b32_e32 v122, v2
	v_mov_b32_e32 v123, v2
	v_mov_b32_e32 v124, v2
	v_mov_b32_e32 v125, v2
	v_mov_b32_e32 v70, v2
	v_mov_b32_e32 v71, v2
	v_mov_b32_e32 v72, v2
	v_mov_b32_e32 v73, v2
	v_mov_b32_e32 v78, v2
	v_mov_b32_e32 v79, v2
	v_mov_b32_e32 v80, v2
	v_mov_b32_e32 v81, v2
	v_mov_b32_e32 v86, v2
	v_mov_b32_e32 v87, v2
	v_mov_b32_e32 v88, v2
	v_mov_b32_e32 v89, v2
	v_mov_b32_e32 v94, v2
	v_mov_b32_e32 v95, v2
	v_mov_b32_e32 v96, v2
	v_mov_b32_e32 v97, v2
	v_mov_b32_e32 v102, v2
	v_mov_b32_e32 v103, v2
	v_mov_b32_e32 v104, v2
	v_mov_b32_e32 v105, v2
	v_mov_b32_e32 v110, v2
	v_mov_b32_e32 v111, v2
	v_mov_b32_e32 v112, v2
	v_mov_b32_e32 v113, v2
	v_mov_b32_e32 v118, v2
	v_mov_b32_e32 v119, v2
	v_mov_b32_e32 v120, v2
	v_mov_b32_e32 v121, v2
	v_mov_b32_e32 v126, v2
	v_mov_b32_e32 v127, v2
	v_mov_b32_e32 v128, v2
	v_mov_b32_e32 v129, v2
	s_lshl_b32 s98, s55, 14
	s_add_u32 s98, s100, s98
	s_addc_u32 s99, s101, 0
	s_mov_b64 vcc, -1
	s_cmpk_gt_u32 s0, 0xff
	s_cbranch_scc0 .Lrs_i2_pre
	s_barrier
.Lrs_i2_pre:
.LBB0_83:
	s_add_u32 s1, s28, 0xfffc0080
	s_addc_u32 s22, s29, -1
	s_add_i32 s23, 0, 0x10000
	v_add_u32_e32 v142, s23, v201
	ds_read_b128 v[130:133], v142
	ds_read_b128 v[134:137], v142 offset:1024
	ds_read_b128 v[138:141], v142 offset:2048
	ds_read_b128 v[142:145], v142 offset:3072
	s_cmp_eq_u32 s60, 12
	s_cselect_b32 s43, s27, s22
	s_cselect_b32 s42, s56, s1
	s_cselect_b32 s31, s7, s59
	s_cselect_b32 s30, s57, s58
	v_lshl_add_u64 v[176:177], s[28:29], 0, v[178:179]
	s_add_i32 m0, s46, 0xc000
	ds_read_b128 v[146:149], v205
	ds_read_b128 v[150:153], v205 offset:1024
	ds_read_b128 v[182:185], v205 offset:2048
	ds_read_b128 v[186:189], v205 offset:3072
	ds_read_b128 v[190:193], v205 offset:4096
	ds_read_b128 v[194:197], v205 offset:5120
	ds_read_b128 v[206:209], v205 offset:6144
	ds_read_b128 v[216:219], v205 offset:7168
	global_load_lds_dwordx4 v[176:177], off
	v_lshl_add_u64 v[176:177], s[28:29], 0, v[180:181]
	s_add_i32 m0, s46, 0xe000
	s_nop 0
	global_load_lds_dwordx4 v[176:177], off
	s_add_i32 s1, 0, 0x14000
	v_add_u32_e32 v168, s1, v201
	ds_read_b128 v[230:233], v168
	ds_read_b128 v[234:237], v168 offset:1024
	ds_read_b128 v[238:241], v168 offset:2048
	ds_read_b128 v[242:245], v168 offset:3072
	s_waitcnt vmcnt(8)
	s_waitcnt lgkmcnt(0)
	s_barrier
	s_setprio 1
	v_mfma_f32_16x16x32_bf16 v[126:129], v[130:133], v[146:149], v[126:129]
	v_mfma_f32_16x16x32_bf16 v[118:121], v[138:141], v[146:149], v[118:121]
	v_mfma_f32_16x16x32_bf16 v[110:113], v[130:133], v[182:185], v[110:113]
	v_mfma_f32_16x16x32_bf16 v[102:105], v[138:141], v[182:185], v[102:105]
	v_mfma_f32_16x16x32_bf16 v[94:97], v[130:133], v[190:193], v[94:97]
	v_mfma_f32_16x16x32_bf16 v[86:89], v[138:141], v[190:193], v[86:89]
	v_mfma_f32_16x16x32_bf16 v[78:81], v[130:133], v[206:209], v[78:81]
	v_mfma_f32_16x16x32_bf16 v[70:73], v[138:141], v[206:209], v[70:73]
	v_mfma_f32_16x16x32_bf16 v[126:129], v[134:137], v[150:153], v[126:129]
	v_mfma_f32_16x16x32_bf16 v[118:121], v[142:145], v[150:153], v[118:121]
	v_mfma_f32_16x16x32_bf16 v[110:113], v[134:137], v[186:189], v[110:113]
	v_mfma_f32_16x16x32_bf16 v[102:105], v[142:145], v[186:189], v[102:105]
	v_mfma_f32_16x16x32_bf16 v[94:97], v[134:137], v[194:197], v[94:97]
	v_mfma_f32_16x16x32_bf16 v[86:89], v[142:145], v[194:197], v[86:89]
	v_mfma_f32_16x16x32_bf16 v[78:81], v[134:137], v[216:219], v[78:81]
	v_mfma_f32_16x16x32_bf16 v[70:73], v[142:145], v[216:219], v[70:73]
	v_mfma_f32_16x16x32_bf16 v[122:125], v[230:233], v[146:149], v[122:125]
	v_mfma_f32_16x16x32_bf16 v[114:117], v[238:241], v[146:149], v[114:117]
	v_mfma_f32_16x16x32_bf16 v[106:109], v[230:233], v[182:185], v[106:109]
	v_mfma_f32_16x16x32_bf16 v[98:101], v[238:241], v[182:185], v[98:101]
	v_mfma_f32_16x16x32_bf16 v[90:93], v[230:233], v[190:193], v[90:93]
	v_mfma_f32_16x16x32_bf16 v[82:85], v[238:241], v[190:193], v[82:85]
	v_mfma_f32_16x16x32_bf16 v[74:77], v[230:233], v[206:209], v[74:77]
	v_mfma_f32_16x16x32_bf16 v[66:69], v[238:241], v[206:209], v[66:69]
	v_mfma_f32_16x16x32_bf16 v[122:125], v[234:237], v[150:153], v[122:125]
	v_mfma_f32_16x16x32_bf16 v[114:117], v[242:245], v[150:153], v[114:117]
	v_mfma_f32_16x16x32_bf16 v[106:109], v[234:237], v[186:189], v[106:109]
	v_mfma_f32_16x16x32_bf16 v[98:101], v[242:245], v[186:189], v[98:101]
	v_mfma_f32_16x16x32_bf16 v[90:93], v[234:237], v[194:197], v[90:93]
	v_mfma_f32_16x16x32_bf16 v[82:85], v[242:245], v[194:197], v[82:85]
	v_mfma_f32_16x16x32_bf16 v[74:77], v[234:237], v[216:219], v[74:77]
	v_mfma_f32_16x16x32_bf16 v[66:69], v[242:245], v[216:219], v[66:69]
	s_setprio 0
	s_barrier
	ds_read_b128 v[146:149], v205 offset:16384
	ds_read_b128 v[150:153], v205 offset:17408
	ds_read_b128 v[182:185], v205 offset:18432
	ds_read_b128 v[186:189], v205 offset:19456
	ds_read_b128 v[190:193], v205 offset:20480
	ds_read_b128 v[194:197], v205 offset:21504
	ds_read_b128 v[206:209], v205 offset:22528
	ds_read_b128 v[216:219], v205 offset:23552
	s_cbranch_vccz .Lss_i2
	v_lshlrev_b32_e32 v176, 4, v167
	s_lshl_b32 m0, s46, 1
	v_add_u32_e32 v176, s46, v176
	s_add_i32 m0, m0, 0x20000
	s_mov_b64 vcc, 0
	global_load_lds_dwordx4 v176, s[98:99]
	global_load_lds_dwordx4 v176, s[98:99] offset:1024
.Lss_i2:
	s_add_i32 s22, s23, s17
	v_lshl_add_u64 v[176:177], s[30:31], 0, v[0:1]
	s_mov_b32 m0, s22
	s_nop 0
	global_load_lds_dwordx4 v[176:177], off
	v_lshl_add_u64 v[202:203], s[30:31], 0, v[154:155]
	s_add_i32 m0, s22, 0x2000
	s_nop 0
	global_load_lds_dwordx4 v[202:203], off
	s_mov_b32 m0, s46
	v_lshl_add_u64 v[220:221], s[42:43], 0, v[158:159]
	global_load_lds_dwordx4 v[220:221], off
	v_lshl_add_u64 v[246:247], s[42:43], 0, v[156:157]
	s_mov_b32 m0, s47
	s_nop 0
	global_load_lds_dwordx4 v[246:247], off
	s_add_u32 s22, s30, 0x40000
	s_addc_u32 s23, s31, 0
	s_add_i32 s1, s1, s17
	s_mov_b32 m0, s1
	s_nop 0
	global_load_lds_dwordx4 v0, s[22:23]
	s_add_i32 m0, s1, 0x2000
	s_nop 0
	global_load_lds_dwordx4 v154, s[22:23]
	s_waitcnt vmcnt(8)
	s_waitcnt lgkmcnt(0)
	s_barrier
	s_setprio 1
	v_mfma_f32_16x16x32_bf16 v[62:65], v[130:133], v[146:149], v[62:65]
	v_mfma_f32_16x16x32_bf16 v[54:57], v[138:141], v[146:149], v[54:57]
	v_mfma_f32_16x16x32_bf16 v[46:49], v[130:133], v[182:185], v[46:49]
	v_mfma_f32_16x16x32_bf16 v[38:41], v[138:141], v[182:185], v[38:41]
	v_mfma_f32_16x16x32_bf16 v[30:33], v[130:133], v[190:193], v[30:33]
	v_mfma_f32_16x16x32_bf16 v[22:25], v[138:141], v[190:193], v[22:25]
	v_mfma_f32_16x16x32_bf16 v[14:17], v[130:133], v[206:209], v[14:17]
	v_mfma_f32_16x16x32_bf16 v[6:9], v[138:141], v[206:209], v[6:9]
	v_mfma_f32_16x16x32_bf16 v[62:65], v[134:137], v[150:153], v[62:65]
	v_mfma_f32_16x16x32_bf16 v[54:57], v[142:145], v[150:153], v[54:57]
	v_mfma_f32_16x16x32_bf16 v[46:49], v[134:137], v[186:189], v[46:49]
	v_mfma_f32_16x16x32_bf16 v[38:41], v[142:145], v[186:189], v[38:41]
	v_mfma_f32_16x16x32_bf16 v[30:33], v[134:137], v[194:197], v[30:33]
	v_mfma_f32_16x16x32_bf16 v[22:25], v[142:145], v[194:197], v[22:25]
	v_mfma_f32_16x16x32_bf16 v[14:17], v[134:137], v[216:219], v[14:17]
	v_mfma_f32_16x16x32_bf16 v[6:9], v[142:145], v[216:219], v[6:9]
	v_mfma_f32_16x16x32_bf16 v[58:61], v[230:233], v[146:149], v[58:61]
	v_mfma_f32_16x16x32_bf16 v[50:53], v[238:241], v[146:149], v[50:53]
	v_mfma_f32_16x16x32_bf16 v[42:45], v[230:233], v[182:185], v[42:45]
	v_mfma_f32_16x16x32_bf16 v[34:37], v[238:241], v[182:185], v[34:37]
	v_mfma_f32_16x16x32_bf16 v[26:29], v[230:233], v[190:193], v[26:29]
	v_mfma_f32_16x16x32_bf16 v[18:21], v[238:241], v[190:193], v[18:21]
	v_mfma_f32_16x16x32_bf16 v[10:13], v[230:233], v[206:209], v[10:13]
	v_mfma_f32_16x16x32_bf16 v[2:5], v[238:241], v[206:209], v[2:5]
	v_mfma_f32_16x16x32_bf16 v[58:61], v[234:237], v[150:153], v[58:61]
	v_mfma_f32_16x16x32_bf16 v[50:53], v[242:245], v[150:153], v[50:53]
	v_mfma_f32_16x16x32_bf16 v[42:45], v[234:237], v[186:189], v[42:45]
	v_mfma_f32_16x16x32_bf16 v[34:37], v[242:245], v[186:189], v[34:37]
	v_mfma_f32_16x16x32_bf16 v[26:29], v[234:237], v[194:197], v[26:29]
	v_mfma_f32_16x16x32_bf16 v[18:21], v[242:245], v[194:197], v[18:21]
	v_mfma_f32_16x16x32_bf16 v[10:13], v[234:237], v[216:219], v[10:13]
	v_mfma_f32_16x16x32_bf16 v[2:5], v[242:245], v[216:219], v[2:5]
	s_setprio 0
	s_barrier
	s_add_i32 s1, 0, 0x18000
	v_add_u32_e32 v142, s1, v201
	ds_read_b128 v[130:133], v142
	ds_read_b128 v[134:137], v142 offset:1024
	ds_read_b128 v[138:141], v142 offset:2048
	ds_read_b128 v[142:145], v142 offset:3072
	s_add_u32 s22, s42, 0x40000
	s_addc_u32 s23, s43, 0
	s_mov_b32 m0, s48
	v_lshl_add_u64 v[230:231], s[22:23], 0, v[158:159]
	ds_read_b128 v[146:149], v205 offset:32768
	ds_read_b128 v[150:153], v205 offset:33792
	ds_read_b128 v[182:185], v205 offset:34816
	ds_read_b128 v[186:189], v205 offset:35840
	ds_read_b128 v[190:193], v205 offset:36864
	ds_read_b128 v[194:197], v205 offset:37888
	ds_read_b128 v[206:209], v205 offset:38912
	ds_read_b128 v[216:219], v205 offset:39936
	global_load_lds_dwordx4 v[230:231], off
	v_lshl_add_u64 v[230:231], s[22:23], 0, v[156:157]
	s_mov_b32 m0, s49
	s_nop 0
	global_load_lds_dwordx4 v[230:231], off
	s_add_i32 s33, 0, 0x1c000
	v_add_u32_e32 v168, s33, v201
	ds_read_b128 v[230:233], v168
	ds_read_b128 v[234:237], v168 offset:1024
	ds_read_b128 v[238:241], v168 offset:2048
	ds_read_b128 v[242:245], v168 offset:3072
	s_waitcnt vmcnt(8)
	s_waitcnt lgkmcnt(0)
	s_barrier
	s_setprio 1
	v_mfma_f32_16x16x32_bf16 v[126:129], v[130:133], v[146:149], v[126:129]
	v_mfma_f32_16x16x32_bf16 v[118:121], v[138:141], v[146:149], v[118:121]
	v_mfma_f32_16x16x32_bf16 v[110:113], v[130:133], v[182:185], v[110:113]
	v_mfma_f32_16x16x32_bf16 v[102:105], v[138:141], v[182:185], v[102:105]
	v_mfma_f32_16x16x32_bf16 v[94:97], v[130:133], v[190:193], v[94:97]
	v_mfma_f32_16x16x32_bf16 v[86:89], v[138:141], v[190:193], v[86:89]
	v_mfma_f32_16x16x32_bf16 v[78:81], v[130:133], v[206:209], v[78:81]
	v_mfma_f32_16x16x32_bf16 v[70:73], v[138:141], v[206:209], v[70:73]
	v_mfma_f32_16x16x32_bf16 v[126:129], v[134:137], v[150:153], v[126:129]
	v_mfma_f32_16x16x32_bf16 v[118:121], v[142:145], v[150:153], v[118:121]
	v_mfma_f32_16x16x32_bf16 v[110:113], v[134:137], v[186:189], v[110:113]
	v_mfma_f32_16x16x32_bf16 v[102:105], v[142:145], v[186:189], v[102:105]
	v_mfma_f32_16x16x32_bf16 v[94:97], v[134:137], v[194:197], v[94:97]
	v_mfma_f32_16x16x32_bf16 v[86:89], v[142:145], v[194:197], v[86:89]
	v_mfma_f32_16x16x32_bf16 v[78:81], v[134:137], v[216:219], v[78:81]
	v_mfma_f32_16x16x32_bf16 v[70:73], v[142:145], v[216:219], v[70:73]
	v_mfma_f32_16x16x32_bf16 v[122:125], v[230:233], v[146:149], v[122:125]
	v_mfma_f32_16x16x32_bf16 v[114:117], v[238:241], v[146:149], v[114:117]
	v_mfma_f32_16x16x32_bf16 v[106:109], v[230:233], v[182:185], v[106:109]
	v_mfma_f32_16x16x32_bf16 v[98:101], v[238:241], v[182:185], v[98:101]
	v_mfma_f32_16x16x32_bf16 v[90:93], v[230:233], v[190:193], v[90:93]
	v_mfma_f32_16x16x32_bf16 v[82:85], v[238:241], v[190:193], v[82:85]
	v_mfma_f32_16x16x32_bf16 v[74:77], v[230:233], v[206:209], v[74:77]
	v_mfma_f32_16x16x32_bf16 v[66:69], v[238:241], v[206:209], v[66:69]
	v_mfma_f32_16x16x32_bf16 v[122:125], v[234:237], v[150:153], v[122:125]
	v_mfma_f32_16x16x32_bf16 v[114:117], v[242:245], v[150:153], v[114:117]
	v_mfma_f32_16x16x32_bf16 v[106:109], v[234:237], v[186:189], v[106:109]
	v_mfma_f32_16x16x32_bf16 v[98:101], v[242:245], v[186:189], v[98:101]
	v_mfma_f32_16x16x32_bf16 v[90:93], v[234:237], v[194:197], v[90:93]
	v_mfma_f32_16x16x32_bf16 v[82:85], v[242:245], v[194:197], v[82:85]
	v_mfma_f32_16x16x32_bf16 v[74:77], v[234:237], v[216:219], v[74:77]
	v_mfma_f32_16x16x32_bf16 v[66:69], v[242:245], v[216:219], v[66:69]
	s_setprio 0
	s_barrier
	ds_read_b128 v[146:149], v205 offset:49152
	ds_read_b128 v[150:153], v205 offset:50176
	ds_read_b128 v[182:185], v205 offset:51200
	ds_read_b128 v[186:189], v205 offset:52224
	ds_read_b128 v[190:193], v205 offset:53248
	ds_read_b128 v[194:197], v205 offset:54272
	ds_read_b128 v[206:209], v205 offset:55296
	ds_read_b128 v[216:219], v205 offset:56320
	s_add_i32 s1, s1, s17
	v_lshl_add_u64 v[176:177], v[176:177], 0, s[12:13]
	s_mov_b32 m0, s1
	s_nop 0
	global_load_lds_dwordx4 v[176:177], off
	v_lshl_add_u64 v[176:177], v[202:203], 0, s[12:13]
	s_add_i32 m0, s1, 0x2000
	s_nop 0
	global_load_lds_dwordx4 v[176:177], off
	s_mov_b32 m0, s20
	v_lshl_add_u64 v[176:177], v[220:221], 0, s[12:13]
	global_load_lds_dwordx4 v[176:177], off
	v_lshl_add_u64 v[176:177], v[246:247], 0, s[12:13]
	s_mov_b32 m0, s21
	s_nop 0
	global_load_lds_dwordx4 v[176:177], off
	s_add_u32 s22, s30, 0x40080
	s_addc_u32 s23, s31, 0
	s_add_i32 s1, s33, s17
	s_mov_b32 m0, s1
	s_nop 0
	global_load_lds_dwordx4 v0, s[22:23]
	s_add_i32 m0, s1, 0x2000
	s_nop 0
	global_load_lds_dwordx4 v154, s[22:23]
	s_waitcnt vmcnt(8)
	s_waitcnt lgkmcnt(0)
	s_barrier
	s_setprio 1
	v_mfma_f32_16x16x32_bf16 v[62:65], v[130:133], v[146:149], v[62:65]
	v_mfma_f32_16x16x32_bf16 v[54:57], v[138:141], v[146:149], v[54:57]
	v_mfma_f32_16x16x32_bf16 v[46:49], v[130:133], v[182:185], v[46:49]
	v_mfma_f32_16x16x32_bf16 v[38:41], v[138:141], v[182:185], v[38:41]
	v_mfma_f32_16x16x32_bf16 v[30:33], v[130:133], v[190:193], v[30:33]
	v_mfma_f32_16x16x32_bf16 v[22:25], v[138:141], v[190:193], v[22:25]
	v_mfma_f32_16x16x32_bf16 v[14:17], v[130:133], v[206:209], v[14:17]
	v_mfma_f32_16x16x32_bf16 v[6:9], v[138:141], v[206:209], v[6:9]
	v_mfma_f32_16x16x32_bf16 v[62:65], v[134:137], v[150:153], v[62:65]
	v_mfma_f32_16x16x32_bf16 v[54:57], v[142:145], v[150:153], v[54:57]
	v_mfma_f32_16x16x32_bf16 v[46:49], v[134:137], v[186:189], v[46:49]
	v_mfma_f32_16x16x32_bf16 v[38:41], v[142:145], v[186:189], v[38:41]
	v_mfma_f32_16x16x32_bf16 v[30:33], v[134:137], v[194:197], v[30:33]
	v_mfma_f32_16x16x32_bf16 v[22:25], v[142:145], v[194:197], v[22:25]
	v_mfma_f32_16x16x32_bf16 v[14:17], v[134:137], v[216:219], v[14:17]
	v_mfma_f32_16x16x32_bf16 v[6:9], v[142:145], v[216:219], v[6:9]
	v_mfma_f32_16x16x32_bf16 v[58:61], v[230:233], v[146:149], v[58:61]
	v_mfma_f32_16x16x32_bf16 v[50:53], v[238:241], v[146:149], v[50:53]
	v_mfma_f32_16x16x32_bf16 v[42:45], v[230:233], v[182:185], v[42:45]
	v_mfma_f32_16x16x32_bf16 v[34:37], v[238:241], v[182:185], v[34:37]
	v_mfma_f32_16x16x32_bf16 v[26:29], v[230:233], v[190:193], v[26:29]
	v_mfma_f32_16x16x32_bf16 v[18:21], v[238:241], v[190:193], v[18:21]
	v_mfma_f32_16x16x32_bf16 v[10:13], v[230:233], v[206:209], v[10:13]
	v_mfma_f32_16x16x32_bf16 v[2:5], v[238:241], v[206:209], v[2:5]
	v_mfma_f32_16x16x32_bf16 v[58:61], v[234:237], v[150:153], v[58:61]
	v_mfma_f32_16x16x32_bf16 v[50:53], v[242:245], v[150:153], v[50:53]
	v_mfma_f32_16x16x32_bf16 v[42:45], v[234:237], v[186:189], v[42:45]
	v_mfma_f32_16x16x32_bf16 v[34:37], v[242:245], v[186:189], v[34:37]
	v_mfma_f32_16x16x32_bf16 v[26:29], v[234:237], v[194:197], v[26:29]
	v_mfma_f32_16x16x32_bf16 v[18:21], v[242:245], v[194:197], v[18:21]
	v_mfma_f32_16x16x32_bf16 v[10:13], v[234:237], v[216:219], v[10:13]
	v_mfma_f32_16x16x32_bf16 v[2:5], v[242:245], v[216:219], v[2:5]
	s_setprio 0
	s_add_i32 s60, s60, 2
	s_add_u32 s28, s28, 0x100
	s_addc_u32 s29, s29, 0
	s_add_u32 s58, s58, 0x100
	s_addc_u32 s59, s59, 0
	s_cmp_gt_u32 s60, 13
	s_barrier
	s_cbranch_scc0 .LBB0_83
	s_cmpk_gt_u32 s0, 0xff
	s_cbranch_scc1 .Lrs_i2_post
	s_barrier
.Lrs_i2_post:
	v_and_b32_e32 v249, 48, v212
	v_lshl_add_u32 v249, v199, 6, v249
	v_add_u32_e32 v249, 0x20000, v249
	v_lshl_add_u32 v196, s55, 8, v199
	v_ashrrev_i32_e32 v197, 31, v196
	v_lshlrev_b64 v[130:131], 6, v[196:197]
	v_or_b32_e32 v194, 16, v196
	v_lshl_add_u64 v[130:131], v[160:161], 0, v[130:131]
	v_ashrrev_i32_e32 v195, 31, v194
	ds_read_b128 v[206:209], v249
	v_lshlrev_b64 v[130:131], 6, v[194:195]
	v_lshl_add_u64 v[130:131], v[160:161], 0, v[130:131]
	ds_read_b128 v[216:219], v249 offset:1024
	v_or_b32_e32 v192, 32, v196
	v_ashrrev_i32_e32 v193, 31, v192
	v_lshlrev_b64 v[130:131], 6, v[192:193]
	v_or_b32_e32 v190, 48, v196
	v_lshl_add_u64 v[130:131], v[160:161], 0, v[130:131]
	v_ashrrev_i32_e32 v191, 31, v190
	ds_read_b128 v[150:153], v249 offset:2048
	v_lshlrev_b64 v[130:131], 6, v[190:191]
	v_lshl_add_u64 v[130:131], v[160:161], 0, v[130:131]
	ds_read_b128 v[146:149], v249 offset:3072
	v_add_u32_e32 v188, 0x80, v196
	v_ashrrev_i32_e32 v189, 31, v188
	v_lshlrev_b64 v[130:131], 6, v[188:189]
	v_add_u32_e32 v186, 0x90, v196
	v_lshl_add_u64 v[130:131], v[160:161], 0, v[130:131]
	v_ashrrev_i32_e32 v187, 31, v186
	ds_read_b128 v[142:145], v249 offset:8192
	v_lshlrev_b64 v[130:131], 6, v[186:187]
	v_lshl_add_u64 v[130:131], v[160:161], 0, v[130:131]
	ds_read_b128 v[138:141], v249 offset:9216
	v_add_u32_e32 v184, 0xa0, v196
	v_ashrrev_i32_e32 v185, 31, v184
	v_lshlrev_b64 v[130:131], 6, v[184:185]
	v_add_u32_e32 v182, 0xb0, v196
	v_lshl_add_u64 v[130:131], v[160:161], 0, v[130:131]
	v_ashrrev_i32_e32 v183, 31, v182
	ds_read_b128 v[134:137], v249 offset:10240
	v_lshlrev_b64 v[130:131], 6, v[182:183]
	v_lshl_add_u64 v[130:131], v[160:161], 0, v[130:131]
	ds_read_b128 v[130:133], v249 offset:11264
	v_and_b32_e32 v169, 64, v212
	v_xor_b32_e32 v168, 16, v212
	v_add_u32_e32 v169, 64, v169
	v_cmp_lt_i32_e32 vcc, v168, v169
	s_mov_b32 s22, 0x358637bd
	s_mov_b32 s55, s26
	v_cndmask_b32_e32 v168, v212, v168, vcc
	v_lshlrev_b32_e32 v185, 2, v168
	v_xor_b32_e32 v168, 32, v212
	v_cmp_lt_i32_e32 vcc, v168, v169
	s_mov_b64 s[30:31], s[44:45]
	s_mov_b64 s[28:29], s[36:37]
	v_cndmask_b32_e32 v168, v212, v168, vcc
	v_lshlrev_b32_e32 v183, 2, v168
	s_waitcnt lgkmcnt(0)
	v_mov_b32_e32 v176, v207
	v_mov_b32_e32 v177, v208
	v_mov_b32_e32 v207, v209
	v_mov_b32_e32 v202, v217
	v_mov_b32_e32 v203, v218
	v_mov_b32_e32 v217, v219
	v_pk_add_f32 v[176:177], v[176:177], v[206:207]
	v_pk_add_f32 v[202:203], v[202:203], v[216:217]
	v_mov_b32_e32 v207, v176
	v_mov_b32_e32 v206, v202
	v_mov_b32_e32 v176, v203
	v_pk_add_f32 v[176:177], v[206:207], v[176:177]
	ds_bpermute_b32 v203, v185, v177
	ds_bpermute_b32 v202, v185, v176
	s_waitcnt lgkmcnt(0)
	v_pk_add_f32 v[176:177], v[176:177], v[202:203]
	ds_bpermute_b32 v203, v183, v177
	ds_bpermute_b32 v202, v183, v176
	s_waitcnt lgkmcnt(0)
	v_pk_add_f32 v[176:177], v[176:177], v[202:203]
	v_mov_b64_e32 v[202:203], s[22:23]
	s_mov_b32 s22, 0x3a800000
	v_pk_fma_f32 v[176:177], v[176:177], s[22:23], v[202:203] op_sel_hi:[1,0,0]
	s_nop 0
	v_mul_f32_e32 v168, 0x4b800000, v177
	v_cmp_gt_f32_e64 s[42:43], s39, v177
	v_cmp_gt_f32_e32 vcc, s39, v176
	s_nop 0
	v_cndmask_b32_e64 v168, v177, v168, s[42:43]
	v_rsq_f32_e32 v168, v168
	v_mov_b32_e32 v177, v152
	v_mov_b32_e32 v152, v147
	v_mov_b32_e32 v147, v149
	v_mul_f32_e32 v169, 0x45800000, v168
	v_cndmask_b32_e64 v200, v168, v169, s[42:43]
	v_mul_f32_e32 v168, 0x4b800000, v176
	v_cndmask_b32_e32 v168, v176, v168, vcc
	v_mov_b32_e32 v176, v151
	v_mov_b32_e32 v151, v153
	v_mov_b32_e32 v153, v148
	v_pk_add_f32 v[150:151], v[176:177], v[150:151]
	v_pk_add_f32 v[146:147], v[152:153], v[146:147]
	v_mov_b32_e32 v149, v150
	v_mov_b32_e32 v148, v146
	v_mov_b32_e32 v150, v147
	v_pk_add_f32 v[146:147], v[148:149], v[150:151]
	ds_bpermute_b32 v149, v185, v147
	ds_bpermute_b32 v148, v185, v146
	v_mov_b32_e32 v150, v143
	v_mov_b32_e32 v151, v144
	v_mov_b32_e32 v143, v145
	v_mov_b32_e32 v144, v139
	v_mov_b32_e32 v145, v140
	v_mov_b32_e32 v139, v141
	v_pk_add_f32 v[142:143], v[150:151], v[142:143]
	v_pk_add_f32 v[138:139], v[144:145], v[138:139]
	s_waitcnt lgkmcnt(0)
	v_pk_add_f32 v[146:147], v[146:147], v[148:149]
	v_mov_b32_e32 v140, v138
	v_mov_b32_e32 v141, v142
	v_mov_b32_e32 v142, v139
	ds_bpermute_b32 v149, v183, v147
	ds_bpermute_b32 v148, v183, v146
	v_pk_add_f32 v[138:139], v[140:141], v[142:143]
	ds_bpermute_b32 v141, v185, v139
	ds_bpermute_b32 v140, v185, v138
	v_mov_b32_e32 v142, v135
	v_mov_b32_e32 v143, v136
	v_mov_b32_e32 v135, v137
	v_mov_b32_e32 v136, v131
	v_mov_b32_e32 v137, v132
	v_mov_b32_e32 v131, v133
	s_waitcnt lgkmcnt(2)
	v_pk_add_f32 v[146:147], v[146:147], v[148:149]
	v_pk_add_f32 v[134:135], v[142:143], v[134:135]
	v_pk_add_f32 v[130:131], v[136:137], v[130:131]
	v_pk_fma_f32 v[146:147], v[146:147], s[22:23], v[202:203] op_sel_hi:[1,0,0]
	s_waitcnt lgkmcnt(0)
	v_pk_add_f32 v[138:139], v[138:139], v[140:141]
	v_mov_b32_e32 v132, v130
	v_mov_b32_e32 v133, v134
	v_mov_b32_e32 v134, v131
	v_mul_f32_e32 v148, 0x4b800000, v147
	v_cmp_gt_f32_e64 s[42:43], s39, v147
	ds_bpermute_b32 v141, v183, v139
	ds_bpermute_b32 v140, v183, v138
	v_pk_add_f32 v[130:131], v[132:133], v[134:135]
	v_cndmask_b32_e64 v147, v147, v148, s[42:43]
	ds_bpermute_b32 v133, v185, v131
	ds_bpermute_b32 v132, v185, v130
	v_rsq_f32_e32 v168, v168
	v_rsq_f32_e32 v147, v147
	s_waitcnt lgkmcnt(2)
	v_pk_add_f32 v[138:139], v[138:139], v[140:141]
	v_pk_mul_f32 v[126:127], v[126:127], v[200:201] op_sel_hi:[1,0]
	v_mul_f32_e32 v169, 0x45800000, v168
	v_mul_f32_e32 v148, 0x45800000, v147
	v_pk_fma_f32 v[138:139], v[138:139], s[22:23], v[202:203] op_sel_hi:[1,0,0]
	s_waitcnt lgkmcnt(0)
	v_pk_add_f32 v[130:131], v[130:131], v[132:133]
	v_cndmask_b32_e32 v198, v168, v169, vcc
	v_cmp_gt_f32_e32 vcc, s39, v146
	v_cndmask_b32_e64 v148, v147, v148, s[42:43]
	v_mul_f32_e32 v147, 0x4b800000, v146
	v_mul_f32_e32 v140, 0x4b800000, v139
	v_cmp_gt_f32_e64 s[42:43], s39, v139
	ds_bpermute_b32 v133, v183, v131
	ds_bpermute_b32 v132, v183, v130
	v_cndmask_b32_e32 v146, v146, v147, vcc
	v_cndmask_b32_e64 v139, v139, v140, s[42:43]
	v_rsq_f32_e32 v146, v146
	v_rsq_f32_e32 v139, v139
	s_waitcnt lgkmcnt(0)
	v_pk_add_f32 v[130:131], v[130:131], v[132:133]
	v_pk_mul_f32 v[122:123], v[122:123], v[200:201] op_sel_hi:[1,0]
	v_mul_f32_e32 v147, 0x45800000, v146
	v_mul_f32_e32 v140, 0x45800000, v139
	v_pk_fma_f32 v[130:131], v[130:131], s[22:23], v[202:203] op_sel_hi:[1,0,0]
	v_cndmask_b32_e32 v146, v146, v147, vcc
	v_cmp_gt_f32_e32 vcc, s39, v138
	v_cndmask_b32_e64 v140, v139, v140, s[42:43]
	v_mul_f32_e32 v139, 0x4b800000, v138
	v_mul_f32_e32 v132, 0x4b800000, v131
	v_cmp_gt_f32_e64 s[42:43], s39, v131
	v_cndmask_b32_e32 v138, v138, v139, vcc
	v_rsq_f32_e32 v138, v138
	v_cndmask_b32_e64 v131, v131, v132, s[42:43]
	v_rsq_f32_e32 v131, v131
	v_pk_mul_f32 v[124:125], v[124:125], v[200:201] op_sel_hi:[1,0]
	v_mul_f32_e32 v139, 0x45800000, v138
	v_cndmask_b32_e32 v138, v138, v139, vcc
	v_mul_f32_e32 v132, 0x45800000, v131
	v_cmp_gt_f32_e32 vcc, s39, v130
	v_cndmask_b32_e64 v132, v131, v132, s[42:43]
	v_mul_f32_e32 v131, 0x4b800000, v130
	v_cndmask_b32_e32 v130, v130, v131, vcc
	v_rsq_f32_e32 v130, v130
	v_pk_mul_f32 v[118:119], v[118:119], v[200:201] op_sel_hi:[1,0]
	v_pk_mul_f32 v[114:115], v[114:115], v[200:201] op_sel_hi:[1,0]
	v_lshl_or_b32 v134, s34, 7, v204
	v_mul_f32_e32 v131, 0x45800000, v130
	v_cndmask_b32_e32 v130, v130, v131, vcc
	v_mul_f32_e32 v131, 0xbfb8aa3b, v126
	v_exp_f32_e32 v131, v131
	v_pk_mul_f32 v[116:117], v[116:117], v[200:201] op_sel_hi:[1,0]
	v_ashrrev_i32_e32 v135, 31, v134
	v_pk_mul_f32 v[110:111], v[110:111], v[198:199] op_sel_hi:[1,0]
	v_add_f32_e32 v131, 1.0, v131
	v_rcp_f32_e32 v136, v131
	v_mul_f32_e32 v131, 0xbfb8aa3b, v127
	v_exp_f32_e32 v131, v131
	v_pk_mul_f32 v[106:107], v[106:107], v[198:199] op_sel_hi:[1,0]
	v_pk_mul_f32 v[108:109], v[108:109], v[198:199] op_sel_hi:[1,0]
	v_pk_mul_f32 v[102:103], v[102:103], v[198:199] op_sel_hi:[1,0]
	v_add_f32_e32 v131, 1.0, v131
	v_rcp_f32_e32 v137, v131
	v_pk_mul_f32 v[98:99], v[98:99], v[198:199] op_sel_hi:[1,0]
	v_pk_mul_f32 v[100:101], v[100:101], v[198:199] op_sel_hi:[1,0]
	v_pk_mul_f32 v[94:95], v[94:95], v[148:149] op_sel_hi:[1,0]
	v_pk_mul_f32 v[126:127], v[126:127], v[136:137]
	v_pk_mul_f32 v[90:91], v[90:91], v[148:149] op_sel_hi:[1,0]
	v_pk_mul_f32 v[122:123], v[122:123], v[126:127]
	v_pk_mul_f32 v[126:127], v[128:129], v[200:201] op_sel_hi:[1,0]
	v_cvt_pk_bf16_f32 v122, v122, v123
	v_mul_f32_e32 v128, 0xbfb8aa3b, v126
	v_mul_f32_e32 v129, 0xbfb8aa3b, v127
	v_exp_f32_e32 v128, v128
	v_exp_f32_e32 v129, v129
	v_pk_mul_f32 v[92:93], v[92:93], v[148:149] op_sel_hi:[1,0]
	v_pk_mul_f32 v[86:87], v[86:87], v[148:149] op_sel_hi:[1,0]
	v_add_f32_e32 v128, 1.0, v128
	v_add_f32_e32 v129, 1.0, v129
	v_rcp_f32_e32 v128, v128
	v_rcp_f32_e32 v129, v129
	v_pk_mul_f32 v[82:83], v[82:83], v[148:149] op_sel_hi:[1,0]
	v_pk_mul_f32 v[84:85], v[84:85], v[148:149] op_sel_hi:[1,0]
	v_pk_mul_f32 v[78:79], v[78:79], v[146:147] op_sel_hi:[1,0]
	v_pk_mul_f32 v[126:127], v[126:127], v[128:129]
	v_pk_mul_f32 v[74:75], v[74:75], v[146:147] op_sel_hi:[1,0]
	v_pk_mul_f32 v[124:125], v[124:125], v[126:127]
	v_pk_mul_f32 v[76:77], v[76:77], v[146:147] op_sel_hi:[1,0]
	v_cvt_pk_bf16_f32 v123, v124, v125
	v_mul_f32_e32 v124, 0xbfb8aa3b, v118
	v_mul_f32_e32 v125, 0xbfb8aa3b, v119
	v_exp_f32_e32 v124, v124
	v_exp_f32_e32 v125, v125
	v_pk_mul_f32 v[70:71], v[70:71], v[146:147] op_sel_hi:[1,0]
	v_pk_mul_f32 v[66:67], v[66:67], v[146:147] op_sel_hi:[1,0]
	v_add_f32_e32 v124, 1.0, v124
	v_add_f32_e32 v125, 1.0, v125
	v_rcp_f32_e32 v124, v124
	v_rcp_f32_e32 v125, v125
	v_pk_mul_f32 v[68:69], v[68:69], v[146:147] op_sel_hi:[1,0]
	v_pk_mul_f32 v[62:63], v[62:63], v[140:141] op_sel_hi:[1,0]
	v_pk_mul_f32 v[58:59], v[58:59], v[140:141] op_sel_hi:[1,0]
	v_pk_mul_f32 v[118:119], v[118:119], v[124:125]
	v_pk_mul_f32 v[60:61], v[60:61], v[140:141] op_sel_hi:[1,0]
	v_pk_mul_f32 v[114:115], v[114:115], v[118:119]
	v_pk_mul_f32 v[118:119], v[120:121], v[200:201] op_sel_hi:[1,0]
	v_cvt_pk_bf16_f32 v124, v114, v115
	v_mul_f32_e32 v120, 0xbfb8aa3b, v118
	v_mul_f32_e32 v121, 0xbfb8aa3b, v119
	v_exp_f32_e32 v120, v120
	v_exp_f32_e32 v121, v121
	v_mov_b64_e32 v[114:115], s[68:69]
	v_pk_mul_f32 v[54:55], v[54:55], v[140:141] op_sel_hi:[1,0]
	v_add_f32_e32 v120, 1.0, v120
	v_add_f32_e32 v121, 1.0, v121
	v_rcp_f32_e32 v120, v120
	v_rcp_f32_e32 v121, v121
	v_pk_mul_f32 v[50:51], v[50:51], v[140:141] op_sel_hi:[1,0]
	v_pk_mul_f32 v[52:53], v[52:53], v[140:141] op_sel_hi:[1,0]
	v_pk_mul_f32 v[46:47], v[46:47], v[138:139] op_sel_hi:[1,0]
	v_pk_mul_f32 v[118:119], v[118:119], v[120:121]
	v_pk_mul_f32 v[42:43], v[42:43], v[138:139] op_sel_hi:[1,0]
	v_pk_mul_f32 v[116:117], v[116:117], v[118:119]
	v_mad_i64_i32 v[118:119], s[22:23], v196, s38, v[114:115]
	v_cvt_pk_bf16_f32 v125, v116, v117
	v_lshlrev_b64 v[116:117], 1, v[134:135]
	v_lshl_add_u64 v[118:119], v[118:119], 0, v[116:117]
	global_store_dwordx4 v[118:119], v[122:125], off
	v_mul_f32_e32 v118, 0xbfb8aa3b, v110
	v_mul_f32_e32 v119, 0xbfb8aa3b, v111
	v_exp_f32_e32 v118, v118
	v_exp_f32_e32 v119, v119
	v_pk_mul_f32 v[44:45], v[44:45], v[138:139] op_sel_hi:[1,0]
	v_pk_mul_f32 v[38:39], v[38:39], v[138:139] op_sel_hi:[1,0]
	v_add_f32_e32 v118, 1.0, v118
	v_add_f32_e32 v119, 1.0, v119
	v_rcp_f32_e32 v118, v118
	v_rcp_f32_e32 v119, v119
	v_pk_mul_f32 v[34:35], v[34:35], v[138:139] op_sel_hi:[1,0]
	v_pk_mul_f32 v[36:37], v[36:37], v[138:139] op_sel_hi:[1,0]
	v_pk_mul_f32 v[30:31], v[30:31], v[132:133] op_sel_hi:[1,0]
	v_pk_mul_f32 v[110:111], v[110:111], v[118:119]
	v_pk_mul_f32 v[26:27], v[26:27], v[132:133] op_sel_hi:[1,0]
	v_pk_mul_f32 v[106:107], v[106:107], v[110:111]
	v_pk_mul_f32 v[110:111], v[112:113], v[198:199] op_sel_hi:[1,0]
	v_cvt_pk_bf16_f32 v106, v106, v107
	v_mul_f32_e32 v112, 0xbfb8aa3b, v110
	v_mul_f32_e32 v113, 0xbfb8aa3b, v111
	v_exp_f32_e32 v112, v112
	v_exp_f32_e32 v113, v113
	v_pk_mul_f32 v[28:29], v[28:29], v[132:133] op_sel_hi:[1,0]
	v_pk_mul_f32 v[22:23], v[22:23], v[132:133] op_sel_hi:[1,0]
	v_add_f32_e32 v112, 1.0, v112
	v_add_f32_e32 v113, 1.0, v113
	v_rcp_f32_e32 v112, v112
	v_rcp_f32_e32 v113, v113
	v_pk_mul_f32 v[18:19], v[18:19], v[132:133] op_sel_hi:[1,0]
	v_pk_mul_f32 v[20:21], v[20:21], v[132:133] op_sel_hi:[1,0]
	v_pk_mul_f32 v[14:15], v[14:15], v[130:131] op_sel_hi:[1,0]
	v_pk_mul_f32 v[110:111], v[110:111], v[112:113]
	v_pk_mul_f32 v[10:11], v[10:11], v[130:131] op_sel_hi:[1,0]
	v_pk_mul_f32 v[108:109], v[108:109], v[110:111]
	v_pk_mul_f32 v[12:13], v[12:13], v[130:131] op_sel_hi:[1,0]
	v_cvt_pk_bf16_f32 v107, v108, v109
	v_mul_f32_e32 v108, 0xbfb8aa3b, v102
	v_mul_f32_e32 v109, 0xbfb8aa3b, v103
	v_exp_f32_e32 v108, v108
	v_exp_f32_e32 v109, v109
	v_pk_mul_f32 v[6:7], v[6:7], v[130:131] op_sel_hi:[1,0]
	v_pk_mul_f32 v[2:3], v[2:3], v[130:131] op_sel_hi:[1,0]
	v_add_f32_e32 v108, 1.0, v108
	v_add_f32_e32 v109, 1.0, v109
	v_rcp_f32_e32 v108, v108
	v_rcp_f32_e32 v109, v109
	v_pk_mul_f32 v[4:5], v[4:5], v[130:131] op_sel_hi:[1,0]
	s_and_b64 vcc, exec, s[40:41]
	s_mov_b32 s34, s6
	v_pk_mul_f32 v[102:103], v[102:103], v[108:109]
	s_nop 0
	v_pk_mul_f32 v[98:99], v[98:99], v[102:103]
	v_pk_mul_f32 v[102:103], v[104:105], v[198:199] op_sel_hi:[1,0]
	v_cvt_pk_bf16_f32 v108, v98, v99
	v_mul_f32_e32 v104, 0xbfb8aa3b, v102
	v_mul_f32_e32 v105, 0xbfb8aa3b, v103
	v_exp_f32_e32 v104, v104
	v_exp_f32_e32 v105, v105
	v_mad_i64_i32 v[98:99], s[22:23], v194, s38, v[114:115]
	v_add_f32_e32 v104, 1.0, v104
	v_add_f32_e32 v105, 1.0, v105
	v_rcp_f32_e32 v104, v104
	v_rcp_f32_e32 v105, v105
	v_lshl_add_u64 v[98:99], v[98:99], 0, v[116:117]
	v_pk_mul_f32 v[102:103], v[102:103], v[104:105]
	s_nop 0
	v_pk_mul_f32 v[100:101], v[100:101], v[102:103]
	s_nop 0
	v_cvt_pk_bf16_f32 v109, v100, v101
	global_store_dwordx4 v[98:99], v[106:109], off
	v_mul_f32_e32 v98, 0xbfb8aa3b, v94
	v_mul_f32_e32 v99, 0xbfb8aa3b, v95
	v_exp_f32_e32 v98, v98
	v_exp_f32_e32 v99, v99
	v_add_f32_e32 v98, 1.0, v98
	v_add_f32_e32 v99, 1.0, v99
	v_rcp_f32_e32 v98, v98
	v_rcp_f32_e32 v99, v99
	s_nop 0
	v_pk_mul_f32 v[94:95], v[94:95], v[98:99]
	s_nop 0
	v_pk_mul_f32 v[90:91], v[90:91], v[94:95]
	v_pk_mul_f32 v[94:95], v[96:97], v[148:149] op_sel_hi:[1,0]
	v_cvt_pk_bf16_f32 v90, v90, v91
	v_mul_f32_e32 v96, 0xbfb8aa3b, v94
	v_mul_f32_e32 v97, 0xbfb8aa3b, v95
	v_exp_f32_e32 v96, v96
	v_exp_f32_e32 v97, v97
	v_add_f32_e32 v96, 1.0, v96
	v_add_f32_e32 v97, 1.0, v97
	v_rcp_f32_e32 v96, v96
	v_rcp_f32_e32 v97, v97
	s_nop 0
	v_pk_mul_f32 v[94:95], v[94:95], v[96:97]
	s_nop 0
	v_pk_mul_f32 v[92:93], v[92:93], v[94:95]
	s_nop 0
	v_cvt_pk_bf16_f32 v91, v92, v93
	v_mul_f32_e32 v92, 0xbfb8aa3b, v86
	v_mul_f32_e32 v93, 0xbfb8aa3b, v87
	v_exp_f32_e32 v92, v92
	v_exp_f32_e32 v93, v93
	v_add_f32_e32 v92, 1.0, v92
	v_add_f32_e32 v93, 1.0, v93
	v_rcp_f32_e32 v92, v92
	v_rcp_f32_e32 v93, v93
	s_nop 0
	v_pk_mul_f32 v[86:87], v[86:87], v[92:93]
	s_nop 0
	v_pk_mul_f32 v[82:83], v[82:83], v[86:87]
	v_pk_mul_f32 v[86:87], v[88:89], v[148:149] op_sel_hi:[1,0]
	v_cvt_pk_bf16_f32 v92, v82, v83
	v_mul_f32_e32 v88, 0xbfb8aa3b, v86
	v_mul_f32_e32 v89, 0xbfb8aa3b, v87
	v_exp_f32_e32 v88, v88
	v_exp_f32_e32 v89, v89
	v_mad_i64_i32 v[82:83], s[22:23], v192, s38, v[114:115]
	v_add_f32_e32 v88, 1.0, v88
	v_add_f32_e32 v89, 1.0, v89
	v_rcp_f32_e32 v88, v88
	v_rcp_f32_e32 v89, v89
	v_lshl_add_u64 v[82:83], v[82:83], 0, v[116:117]
	v_pk_mul_f32 v[86:87], v[86:87], v[88:89]
	s_nop 0
	v_pk_mul_f32 v[84:85], v[84:85], v[86:87]
	s_nop 0
	v_cvt_pk_bf16_f32 v93, v84, v85
	global_store_dwordx4 v[82:83], v[90:93], off
	v_mul_f32_e32 v82, 0xbfb8aa3b, v78
	v_mul_f32_e32 v83, 0xbfb8aa3b, v79
	v_exp_f32_e32 v82, v82
	v_exp_f32_e32 v83, v83
	v_add_f32_e32 v82, 1.0, v82
	v_add_f32_e32 v83, 1.0, v83
	v_rcp_f32_e32 v82, v82
	v_rcp_f32_e32 v83, v83
	s_nop 0
	v_pk_mul_f32 v[78:79], v[78:79], v[82:83]
	s_nop 0
	v_pk_mul_f32 v[74:75], v[74:75], v[78:79]
	v_pk_mul_f32 v[78:79], v[80:81], v[146:147] op_sel_hi:[1,0]
	v_cvt_pk_bf16_f32 v74, v74, v75
	v_mul_f32_e32 v80, 0xbfb8aa3b, v78
	v_mul_f32_e32 v81, 0xbfb8aa3b, v79
	v_exp_f32_e32 v80, v80
	v_exp_f32_e32 v81, v81
	v_add_f32_e32 v80, 1.0, v80
	v_add_f32_e32 v81, 1.0, v81
	v_rcp_f32_e32 v80, v80
	v_rcp_f32_e32 v81, v81
	s_nop 0
	v_pk_mul_f32 v[78:79], v[78:79], v[80:81]
	s_nop 0
	v_pk_mul_f32 v[76:77], v[76:77], v[78:79]
	s_nop 0
	v_cvt_pk_bf16_f32 v75, v76, v77
	v_mul_f32_e32 v76, 0xbfb8aa3b, v70
	v_mul_f32_e32 v77, 0xbfb8aa3b, v71
	v_exp_f32_e32 v76, v76
	v_exp_f32_e32 v77, v77
	v_add_f32_e32 v76, 1.0, v76
	v_add_f32_e32 v77, 1.0, v77
	v_rcp_f32_e32 v76, v76
	v_rcp_f32_e32 v77, v77
	s_nop 0
	v_pk_mul_f32 v[70:71], v[70:71], v[76:77]
	s_nop 0
	v_pk_mul_f32 v[66:67], v[66:67], v[70:71]
	v_pk_mul_f32 v[70:71], v[72:73], v[146:147] op_sel_hi:[1,0]
	v_cvt_pk_bf16_f32 v76, v66, v67
	v_mul_f32_e32 v72, 0xbfb8aa3b, v70
	v_mul_f32_e32 v73, 0xbfb8aa3b, v71
	v_exp_f32_e32 v72, v72
	v_exp_f32_e32 v73, v73
	v_mad_i64_i32 v[66:67], s[22:23], v190, s38, v[114:115]
	v_add_f32_e32 v72, 1.0, v72
	v_add_f32_e32 v73, 1.0, v73
	v_rcp_f32_e32 v72, v72
	v_rcp_f32_e32 v73, v73
	v_lshl_add_u64 v[66:67], v[66:67], 0, v[116:117]
	v_pk_mul_f32 v[70:71], v[70:71], v[72:73]
	s_nop 0
	v_pk_mul_f32 v[68:69], v[68:69], v[70:71]
	s_nop 0
	v_cvt_pk_bf16_f32 v77, v68, v69
	global_store_dwordx4 v[66:67], v[74:77], off
	v_mul_f32_e32 v66, 0xbfb8aa3b, v62
	v_mul_f32_e32 v67, 0xbfb8aa3b, v63
	v_exp_f32_e32 v66, v66
	v_exp_f32_e32 v67, v67
	v_add_f32_e32 v66, 1.0, v66
	v_add_f32_e32 v67, 1.0, v67
	v_rcp_f32_e32 v66, v66
	v_rcp_f32_e32 v67, v67
	s_nop 0
	v_pk_mul_f32 v[62:63], v[62:63], v[66:67]
	s_nop 0
	v_pk_mul_f32 v[58:59], v[58:59], v[62:63]
	v_pk_mul_f32 v[62:63], v[64:65], v[140:141] op_sel_hi:[1,0]
	v_cvt_pk_bf16_f32 v58, v58, v59
	v_mul_f32_e32 v64, 0xbfb8aa3b, v62
	v_mul_f32_e32 v65, 0xbfb8aa3b, v63
	v_exp_f32_e32 v64, v64
	v_exp_f32_e32 v65, v65
	v_add_f32_e32 v64, 1.0, v64
	v_add_f32_e32 v65, 1.0, v65
	v_rcp_f32_e32 v64, v64
	v_rcp_f32_e32 v65, v65
	s_nop 0
	v_pk_mul_f32 v[62:63], v[62:63], v[64:65]
	s_nop 0
	v_pk_mul_f32 v[60:61], v[60:61], v[62:63]
	s_nop 0
	v_cvt_pk_bf16_f32 v59, v60, v61
	v_mul_f32_e32 v60, 0xbfb8aa3b, v54
	v_mul_f32_e32 v61, 0xbfb8aa3b, v55
	v_exp_f32_e32 v60, v60
	v_exp_f32_e32 v61, v61
	v_add_f32_e32 v60, 1.0, v60
	v_add_f32_e32 v61, 1.0, v61
	v_rcp_f32_e32 v60, v60
	v_rcp_f32_e32 v61, v61
	s_nop 0
	v_pk_mul_f32 v[54:55], v[54:55], v[60:61]
	s_nop 0
	v_pk_mul_f32 v[50:51], v[50:51], v[54:55]
	v_pk_mul_f32 v[54:55], v[56:57], v[140:141] op_sel_hi:[1,0]
	v_cvt_pk_bf16_f32 v60, v50, v51
	v_mul_f32_e32 v56, 0xbfb8aa3b, v54
	v_mul_f32_e32 v57, 0xbfb8aa3b, v55
	v_exp_f32_e32 v56, v56
	v_exp_f32_e32 v57, v57
	v_mad_i64_i32 v[50:51], s[22:23], v188, s38, v[114:115]
	v_add_f32_e32 v56, 1.0, v56
	v_add_f32_e32 v57, 1.0, v57
	v_rcp_f32_e32 v56, v56
	v_rcp_f32_e32 v57, v57
	v_lshl_add_u64 v[50:51], v[50:51], 0, v[116:117]
	v_pk_mul_f32 v[54:55], v[54:55], v[56:57]
	s_nop 0
	v_pk_mul_f32 v[52:53], v[52:53], v[54:55]
	s_nop 0
	v_cvt_pk_bf16_f32 v61, v52, v53
	global_store_dwordx4 v[50:51], v[58:61], off
	v_mul_f32_e32 v50, 0xbfb8aa3b, v46
	v_mul_f32_e32 v51, 0xbfb8aa3b, v47
	v_exp_f32_e32 v50, v50
	v_exp_f32_e32 v51, v51
	v_add_f32_e32 v50, 1.0, v50
	v_add_f32_e32 v51, 1.0, v51
	v_rcp_f32_e32 v50, v50
	v_rcp_f32_e32 v51, v51
	s_nop 0
	v_pk_mul_f32 v[46:47], v[46:47], v[50:51]
	s_nop 0
	v_pk_mul_f32 v[42:43], v[42:43], v[46:47]
	v_pk_mul_f32 v[46:47], v[48:49], v[138:139] op_sel_hi:[1,0]
	v_cvt_pk_bf16_f32 v42, v42, v43
	v_mul_f32_e32 v48, 0xbfb8aa3b, v46
	v_mul_f32_e32 v49, 0xbfb8aa3b, v47
	v_exp_f32_e32 v48, v48
	v_exp_f32_e32 v49, v49
	v_add_f32_e32 v48, 1.0, v48
	v_add_f32_e32 v49, 1.0, v49
	v_rcp_f32_e32 v48, v48
	v_rcp_f32_e32 v49, v49
	s_nop 0
	v_pk_mul_f32 v[46:47], v[46:47], v[48:49]
	s_nop 0
	v_pk_mul_f32 v[44:45], v[44:45], v[46:47]
	s_nop 0
	v_cvt_pk_bf16_f32 v43, v44, v45
	v_mul_f32_e32 v44, 0xbfb8aa3b, v38
	v_mul_f32_e32 v45, 0xbfb8aa3b, v39
	v_exp_f32_e32 v44, v44
	v_exp_f32_e32 v45, v45
	v_add_f32_e32 v44, 1.0, v44
	v_add_f32_e32 v45, 1.0, v45
	v_rcp_f32_e32 v44, v44
	v_rcp_f32_e32 v45, v45
	s_nop 0
	v_pk_mul_f32 v[38:39], v[38:39], v[44:45]
	s_nop 0
	v_pk_mul_f32 v[34:35], v[34:35], v[38:39]
	v_pk_mul_f32 v[38:39], v[40:41], v[138:139] op_sel_hi:[1,0]
	v_cvt_pk_bf16_f32 v44, v34, v35
	v_mul_f32_e32 v40, 0xbfb8aa3b, v38
	v_mul_f32_e32 v41, 0xbfb8aa3b, v39
	v_exp_f32_e32 v40, v40
	v_exp_f32_e32 v41, v41
	v_mad_i64_i32 v[34:35], s[22:23], v186, s38, v[114:115]
	v_add_f32_e32 v40, 1.0, v40
	v_add_f32_e32 v41, 1.0, v41
	v_rcp_f32_e32 v40, v40
	v_rcp_f32_e32 v41, v41
	v_lshl_add_u64 v[34:35], v[34:35], 0, v[116:117]
	v_pk_mul_f32 v[38:39], v[38:39], v[40:41]
	s_nop 0
	v_pk_mul_f32 v[36:37], v[36:37], v[38:39]
	s_nop 0
	v_cvt_pk_bf16_f32 v45, v36, v37
	global_store_dwordx4 v[34:35], v[42:45], off
	v_mul_f32_e32 v34, 0xbfb8aa3b, v30
	v_mul_f32_e32 v35, 0xbfb8aa3b, v31
	v_exp_f32_e32 v34, v34
	v_exp_f32_e32 v35, v35
	v_add_f32_e32 v34, 1.0, v34
	v_add_f32_e32 v35, 1.0, v35
	v_rcp_f32_e32 v34, v34
	v_rcp_f32_e32 v35, v35
	s_nop 0
	v_pk_mul_f32 v[30:31], v[30:31], v[34:35]
	s_nop 0
	v_pk_mul_f32 v[26:27], v[26:27], v[30:31]
	v_pk_mul_f32 v[30:31], v[32:33], v[132:133] op_sel_hi:[1,0]
	v_cvt_pk_bf16_f32 v26, v26, v27
	v_mul_f32_e32 v32, 0xbfb8aa3b, v30
	v_mul_f32_e32 v33, 0xbfb8aa3b, v31
	v_exp_f32_e32 v32, v32
	v_exp_f32_e32 v33, v33
	v_add_f32_e32 v32, 1.0, v32
	v_add_f32_e32 v33, 1.0, v33
	v_rcp_f32_e32 v32, v32
	v_rcp_f32_e32 v33, v33
	s_nop 0
	v_pk_mul_f32 v[30:31], v[30:31], v[32:33]
	s_nop 0
	v_pk_mul_f32 v[28:29], v[28:29], v[30:31]
	s_nop 0
	v_cvt_pk_bf16_f32 v27, v28, v29
	v_mul_f32_e32 v28, 0xbfb8aa3b, v22
	v_mul_f32_e32 v29, 0xbfb8aa3b, v23
	v_exp_f32_e32 v28, v28
	v_exp_f32_e32 v29, v29
	v_add_f32_e32 v28, 1.0, v28
	v_add_f32_e32 v29, 1.0, v29
	v_rcp_f32_e32 v28, v28
	v_rcp_f32_e32 v29, v29
	s_nop 0
	v_pk_mul_f32 v[22:23], v[22:23], v[28:29]
	s_nop 0
	v_pk_mul_f32 v[18:19], v[18:19], v[22:23]
	v_pk_mul_f32 v[22:23], v[24:25], v[132:133] op_sel_hi:[1,0]
	v_cvt_pk_bf16_f32 v28, v18, v19
	v_mul_f32_e32 v24, 0xbfb8aa3b, v22
	v_mul_f32_e32 v25, 0xbfb8aa3b, v23
	v_exp_f32_e32 v24, v24
	v_exp_f32_e32 v25, v25
	v_mad_i64_i32 v[18:19], s[22:23], v184, s38, v[114:115]
	v_add_f32_e32 v24, 1.0, v24
	v_add_f32_e32 v25, 1.0, v25
	v_rcp_f32_e32 v24, v24
	v_rcp_f32_e32 v25, v25
	v_lshl_add_u64 v[18:19], v[18:19], 0, v[116:117]
	v_pk_mul_f32 v[22:23], v[22:23], v[24:25]
	s_nop 0
	v_pk_mul_f32 v[20:21], v[20:21], v[22:23]
	s_nop 0
	v_cvt_pk_bf16_f32 v29, v20, v21
	global_store_dwordx4 v[18:19], v[26:29], off
	v_mul_f32_e32 v18, 0xbfb8aa3b, v14
	v_mul_f32_e32 v19, 0xbfb8aa3b, v15
	v_exp_f32_e32 v18, v18
	v_exp_f32_e32 v19, v19
	v_add_f32_e32 v18, 1.0, v18
	v_add_f32_e32 v19, 1.0, v19
	v_rcp_f32_e32 v18, v18
	v_rcp_f32_e32 v19, v19
	s_nop 0
	v_pk_mul_f32 v[14:15], v[14:15], v[18:19]
	s_nop 0
	v_pk_mul_f32 v[10:11], v[10:11], v[14:15]
	v_pk_mul_f32 v[14:15], v[16:17], v[130:131] op_sel_hi:[1,0]
	v_cvt_pk_bf16_f32 v10, v10, v11
	v_mul_f32_e32 v16, 0xbfb8aa3b, v14
	v_mul_f32_e32 v17, 0xbfb8aa3b, v15
	v_exp_f32_e32 v16, v16
	v_exp_f32_e32 v17, v17
	v_add_f32_e32 v16, 1.0, v16
	v_add_f32_e32 v17, 1.0, v17
	v_rcp_f32_e32 v16, v16
	v_rcp_f32_e32 v17, v17
	s_nop 0
	v_pk_mul_f32 v[14:15], v[14:15], v[16:17]
	s_nop 0
	v_pk_mul_f32 v[12:13], v[12:13], v[14:15]
	s_nop 0
	v_cvt_pk_bf16_f32 v11, v12, v13
	v_mul_f32_e32 v12, 0xbfb8aa3b, v6
	v_mul_f32_e32 v13, 0xbfb8aa3b, v7
	v_exp_f32_e32 v12, v12
	v_exp_f32_e32 v13, v13
	v_add_f32_e32 v12, 1.0, v12
	v_add_f32_e32 v13, 1.0, v13
	v_rcp_f32_e32 v12, v12
	v_rcp_f32_e32 v13, v13
	s_nop 0
	v_pk_mul_f32 v[6:7], v[6:7], v[12:13]
	s_nop 0
	v_pk_mul_f32 v[2:3], v[2:3], v[6:7]
	v_pk_mul_f32 v[6:7], v[8:9], v[130:131] op_sel_hi:[1,0]
	v_cvt_pk_bf16_f32 v12, v2, v3
	v_mul_f32_e32 v8, 0xbfb8aa3b, v6
	v_mul_f32_e32 v9, 0xbfb8aa3b, v7
	v_exp_f32_e32 v8, v8
	v_exp_f32_e32 v9, v9
	v_mad_i64_i32 v[2:3], s[22:23], v182, s38, v[114:115]
	v_add_f32_e32 v8, 1.0, v8
	v_add_f32_e32 v9, 1.0, v9
	v_rcp_f32_e32 v8, v8
	v_rcp_f32_e32 v9, v9
	v_lshl_add_u64 v[2:3], v[2:3], 0, v[116:117]
	v_pk_mul_f32 v[6:7], v[6:7], v[8:9]
	s_nop 0
	v_pk_mul_f32 v[4:5], v[4:5], v[6:7]
	s_nop 0
	v_cvt_pk_bf16_f32 v13, v4, v5
	global_store_dwordx4 v[2:3], v[10:13], off
	s_cbranch_vccz .LBB0_80
	s_waitcnt vmcnt(0)
	s_cmpk_gt_u32 s0, 0xff
	s_cbranch_scc1 .LBB0_87
	s_nop 0

.LBB0_284:
	s_and_b32 s1, s7, 3
	s_add_i32 m0, s16, 0x18000
	v_lshl_add_u64 v[8:9], v[8:9], 0, s[12:13]
	s_lshl_b32 s7, s6, 13
	s_lshl_b32 s24, s1, 12
	s_waitcnt vmcnt(2)
	s_barrier
	global_load_lds_dwordx4 v[8:9], off
	v_lshl_add_u64 v[6:7], v[6:7], 0, s[12:13]
	s_add_i32 m0, s16, 0x1a000
	s_add_i32 s34, s16, 0x8000
	s_add_i32 s46, s16, 0xa000
	global_load_lds_dwordx4 v[6:7], off
	v_lshl_add_u64 v[4:5], v[4:5], 0, s[12:13]
	s_mov_b32 m0, s34
	s_add_u32 s22, s30, 0x40080
	global_load_lds_dwordx4 v[4:5], off
	v_lshl_add_u64 v[2:3], v[2:3], 0, s[12:13]
	s_mov_b32 m0, s46
	s_addc_u32 s23, s31, 0
	global_load_lds_dwordx4 v[2:3], off
	s_add_i32 m0, s16, 0x1c000
	v_lshl_add_u64 v[2:3], s[22:23], 0, v[0:1]
	global_load_lds_dwordx4 v[2:3], off
	v_lshl_add_u64 v[2:3], s[22:23], 0, v[178:179]
	s_add_i32 m0, s16, 0x1e000
	v_bfe_u32 v4, v13, 4, 2
	global_load_lds_dwordx4 v[2:3], off
	v_and_b32_e32 v3, 15, v13
	v_lshlrev_b32_e32 v2, 4, v4
	v_lshlrev_b32_e32 v6, 2, v13
	v_lshl_or_b32 v216, s6, 6, v3
	v_lshl_or_b32 v3, v3, 6, v2
	v_and_b32_e32 v6, 32, v6
	v_lshlrev_b32_e32 v5, 3, v4
	v_bitop3_b32 v7, v3, s7, v6 bitop3:0xde
	v_readlane_b32 s6, v254, 50
	v_lshl_or_b32 v218, s1, 5, v5
	v_lshlrev_b32_e32 v4, 5, v4
	v_mov_b32_e32 v5, v1
	v_readlane_b32 s7, v254, 51
	v_bitop3_b32 v217, v3, s24, v6 bitop3:0xde
	v_mov_b32_e32 v3, v1
	v_lshl_add_u64 v[184:185], s[6:7], 0, v[4:5]
	v_readlane_b32 s6, v254, 37
	v_readlane_b32 s7, v254, 38
	s_waitcnt vmcnt(6)
	s_barrier
	s_cmp_eq_u32 s1, 0
	s_mov_b64 s[100:101], s[6:7]
	v_lshl_add_u64 v[186:187], s[6:7], 0, v[2:3]
	v_readlane_b32 s6, v254, 31
	v_lshlrev_b32_e32 v2, 14, v15
	v_readlane_b32 s7, v254, 32
	v_and_b32_e32 v2, 0xffff8000, v2
	s_load_dwordx2 s[6:7], s[6:7], 0x28
	v_lshl_add_u32 v2, v14, 11, v2
	v_and_b32_e32 v3, 1, v15
	v_lshl_or_b32 v2, v3, 6, v2
	v_lshl_add_u32 v190, v16, 1, v2
	v_lshlrev_b32_e32 v2, 14, v10
	v_and_b32_e32 v2, 0xffff8000, v2
	v_lshl_add_u32 v2, v11, 11, v2
	v_and_b32_e32 v3, 1, v10
	s_waitcnt lgkmcnt(0)
	v_lshl_add_u64 v[188:189], s[6:7], 0, v[4:5]
	v_lshl_or_b32 v2, v3, 6, v2
	v_readlane_b32 s6, v253, 17
	s_mov_b32 s47, 0
	s_cselect_b64 s[24:25], -1, 0
	v_mov_b32_e32 v191, v1
	v_lshl_add_u32 v192, v12, 1, v2
	v_mov_b32_e32 v193, v1
	v_add_u32_e32 v219, 0, v7
	v_readlane_b32 s48, v253, 14
	s_mov_b32 s49, s6
	v_readlane_b32 s7, v253, 18
	s_branch .LBB0_286

.LBB0_288:
	s_ashr_i32 s27, s26, 31
	s_lshl_b64 s[22:23], s[26:27], 19
	v_cmp_lt_i64_e32 vcc, s[28:29], v[170:171]
	s_add_u32 s28, s96, s22
	s_addc_u32 s29, s97, s23
	s_and_b64 s[22:23], vcc, exec
	s_cselect_b32 s27, s29, s43
	s_cselect_b32 s50, s28, s42
	s_ashr_i32 s7, s6, 31
	s_lshl_b64 s[22:23], s[6:7], 19
	s_add_u32 s36, s10, s22
	s_addc_u32 s37, s11, s23
	s_and_b64 s[22:23], vcc, exec
	s_cselect_b32 s7, s37, s31
	s_cselect_b32 s51, s36, s30
	s_add_u32 s42, s42, 0x40080
	s_addc_u32 s43, s43, 0
	s_add_u32 s52, s30, 0x100
	v_mov_b32_e32 v2, 0
	s_addc_u32 s53, s31, 0
	s_mov_b32 s54, -2
	v_mov_b32_e32 v3, v2
	v_mov_b32_e32 v4, v2
	v_mov_b32_e32 v5, v2
	v_mov_b32_e32 v6, v2
	v_mov_b32_e32 v7, v2
	v_mov_b32_e32 v8, v2
	v_mov_b32_e32 v9, v2
	v_mov_b32_e32 v10, v2
	v_mov_b32_e32 v11, v2
	v_mov_b32_e32 v12, v2
	v_mov_b32_e32 v13, v2
	v_mov_b32_e32 v18, v2
	v_mov_b32_e32 v19, v2
	v_mov_b32_e32 v20, v2
	v_mov_b32_e32 v21, v2
	v_mov_b32_e32 v26, v2
	v_mov_b32_e32 v27, v2
	v_mov_b32_e32 v28, v2
	v_mov_b32_e32 v29, v2
	v_mov_b32_e32 v34, v2
	v_mov_b32_e32 v35, v2
	v_mov_b32_e32 v36, v2
	v_mov_b32_e32 v37, v2
	v_mov_b32_e32 v42, v2
	v_mov_b32_e32 v43, v2
	v_mov_b32_e32 v44, v2
	v_mov_b32_e32 v45, v2
	v_mov_b32_e32 v50, v2
	v_mov_b32_e32 v51, v2
	v_mov_b32_e32 v52, v2
	v_mov_b32_e32 v53, v2
	v_mov_b32_e32 v14, v2
	v_mov_b32_e32 v15, v2
	v_mov_b32_e32 v16, v2
	v_mov_b32_e32 v17, v2
	v_mov_b32_e32 v22, v2
	v_mov_b32_e32 v23, v2
	v_mov_b32_e32 v24, v2
	v_mov_b32_e32 v25, v2
	v_mov_b32_e32 v30, v2
	v_mov_b32_e32 v31, v2
	v_mov_b32_e32 v32, v2
	v_mov_b32_e32 v33, v2
	v_mov_b32_e32 v38, v2
	v_mov_b32_e32 v39, v2
	v_mov_b32_e32 v40, v2
	v_mov_b32_e32 v41, v2
	v_mov_b32_e32 v46, v2
	v_mov_b32_e32 v47, v2
	v_mov_b32_e32 v48, v2
	v_mov_b32_e32 v49, v2
	v_mov_b32_e32 v54, v2
	v_mov_b32_e32 v55, v2
	v_mov_b32_e32 v56, v2
	v_mov_b32_e32 v57, v2
	v_mov_b32_e32 v58, v2
	v_mov_b32_e32 v59, v2
	v_mov_b32_e32 v60, v2
	v_mov_b32_e32 v61, v2
	v_mov_b32_e32 v62, v2
	v_mov_b32_e32 v63, v2
	v_mov_b32_e32 v64, v2
	v_mov_b32_e32 v65, v2
	v_mov_b32_e32 v66, v2
	v_mov_b32_e32 v67, v2
	v_mov_b32_e32 v68, v2
	v_mov_b32_e32 v69, v2
	v_mov_b32_e32 v70, v2
	v_mov_b32_e32 v71, v2
	v_mov_b32_e32 v72, v2
	v_mov_b32_e32 v73, v2
	v_mov_b32_e32 v74, v2
	v_mov_b32_e32 v75, v2
	v_mov_b32_e32 v76, v2
	v_mov_b32_e32 v77, v2
	v_mov_b32_e32 v82, v2
	v_mov_b32_e32 v83, v2
	v_mov_b32_e32 v84, v2
	v_mov_b32_e32 v85, v2
	v_mov_b32_e32 v90, v2
	v_mov_b32_e32 v91, v2
	v_mov_b32_e32 v92, v2
	v_mov_b32_e32 v93, v2
	v_mov_b32_e32 v98, v2
	v_mov_b32_e32 v99, v2
	v_mov_b32_e32 v100, v2
	v_mov_b32_e32 v101, v2
	v_mov_b32_e32 v106, v2
	v_mov_b32_e32 v107, v2
	v_mov_b32_e32 v108, v2
	v_mov_b32_e32 v109, v2
	v_mov_b32_e32 v114, v2
	v_mov_b32_e32 v115, v2
	v_mov_b32_e32 v116, v2
	v_mov_b32_e32 v117, v2
	v_mov_b32_e32 v78, v2
	v_mov_b32_e32 v79, v2
	v_mov_b32_e32 v80, v2
	v_mov_b32_e32 v81, v2
	v_mov_b32_e32 v86, v2
	v_mov_b32_e32 v87, v2
	v_mov_b32_e32 v88, v2
	v_mov_b32_e32 v89, v2
	v_mov_b32_e32 v94, v2
	v_mov_b32_e32 v95, v2
	v_mov_b32_e32 v96, v2
	v_mov_b32_e32 v97, v2
	v_mov_b32_e32 v102, v2
	v_mov_b32_e32 v103, v2
	v_mov_b32_e32 v104, v2
	v_mov_b32_e32 v105, v2
	v_mov_b32_e32 v110, v2
	v_mov_b32_e32 v111, v2
	v_mov_b32_e32 v112, v2
	v_mov_b32_e32 v113, v2
	v_mov_b32_e32 v118, v2
	v_mov_b32_e32 v119, v2
	v_mov_b32_e32 v120, v2
	v_mov_b32_e32 v121, v2
	v_mov_b32_e32 v122, v2
	v_mov_b32_e32 v123, v2
	v_mov_b32_e32 v124, v2
	v_mov_b32_e32 v125, v2
	v_mov_b32_e32 v126, v2
	v_mov_b32_e32 v127, v2
	v_mov_b32_e32 v128, v2
	v_mov_b32_e32 v129, v2
	s_lshl_b32 s98, s49, 14
	s_add_u32 s98, s100, s98
	s_addc_u32 s99, s101, 0
	s_mov_b64 vcc, -1
	s_cmpk_gt_u32 s0, 0xff
	s_cbranch_scc0 .Lrs_proj0_pre
	s_barrier
.Lrs_proj0_pre:
.LBB0_289:
	s_add_u32 s1, s42, 0xfffc0080
	s_addc_u32 s22, s43, -1
	s_add_i32 s23, 0, 0x10000
	v_add_u32_e32 v142, s23, v217
	ds_read_b128 v[130:133], v142
	ds_read_b128 v[134:137], v142 offset:1024
	ds_read_b128 v[138:141], v142 offset:2048
	ds_read_b128 v[142:145], v142 offset:3072
	s_cmp_eq_u32 s54, 12
	s_cselect_b32 s45, s27, s22
	s_cselect_b32 s44, s50, s1
	s_cselect_b32 s31, s7, s53
	s_cselect_b32 s30, s51, s52
	v_lshl_add_u64 v[176:177], s[42:43], 0, v[190:191]
	s_add_i32 m0, s16, 0xc000
	ds_read_b128 v[146:149], v219
	ds_read_b128 v[150:153], v219 offset:1024
	ds_read_b128 v[154:157], v219 offset:2048
	ds_read_b128 v[158:161], v219 offset:3072
	ds_read_b128 v[194:197], v219 offset:4096
	ds_read_b128 v[198:201], v219 offset:5120
	ds_read_b128 v[202:205], v219 offset:6144
	ds_read_b128 v[206:209], v219 offset:7168
	global_load_lds_dwordx4 v[176:177], off
	v_lshl_add_u64 v[176:177], s[42:43], 0, v[192:193]
	s_add_i32 m0, s16, 0xe000
	s_nop 0
	global_load_lds_dwordx4 v[176:177], off
	s_add_i32 s1, 0, 0x14000
	v_add_u32_e32 v168, s1, v217
	ds_read_b128 v[230:233], v168
	ds_read_b128 v[234:237], v168 offset:1024
	ds_read_b128 v[238:241], v168 offset:2048
	ds_read_b128 v[242:245], v168 offset:3072
	s_waitcnt vmcnt(8)
	s_waitcnt lgkmcnt(0)
	s_barrier
	s_setprio 1
	v_mfma_f32_16x16x32_bf16 v[126:129], v[130:133], v[146:149], v[126:129]
	v_mfma_f32_16x16x32_bf16 v[122:125], v[138:141], v[146:149], v[122:125]
	v_mfma_f32_16x16x32_bf16 v[118:121], v[130:133], v[154:157], v[118:121]
	v_mfma_f32_16x16x32_bf16 v[110:113], v[138:141], v[154:157], v[110:113]
	v_mfma_f32_16x16x32_bf16 v[102:105], v[130:133], v[194:197], v[102:105]
	v_mfma_f32_16x16x32_bf16 v[94:97], v[138:141], v[194:197], v[94:97]
	v_mfma_f32_16x16x32_bf16 v[86:89], v[130:133], v[202:205], v[86:89]
	v_mfma_f32_16x16x32_bf16 v[78:81], v[138:141], v[202:205], v[78:81]
	v_mfma_f32_16x16x32_bf16 v[126:129], v[134:137], v[150:153], v[126:129]
	v_mfma_f32_16x16x32_bf16 v[122:125], v[142:145], v[150:153], v[122:125]
	v_mfma_f32_16x16x32_bf16 v[118:121], v[134:137], v[158:161], v[118:121]
	v_mfma_f32_16x16x32_bf16 v[110:113], v[142:145], v[158:161], v[110:113]
	v_mfma_f32_16x16x32_bf16 v[102:105], v[134:137], v[198:201], v[102:105]
	v_mfma_f32_16x16x32_bf16 v[94:97], v[142:145], v[198:201], v[94:97]
	v_mfma_f32_16x16x32_bf16 v[86:89], v[134:137], v[206:209], v[86:89]
	v_mfma_f32_16x16x32_bf16 v[78:81], v[142:145], v[206:209], v[78:81]
	v_mfma_f32_16x16x32_bf16 v[114:117], v[230:233], v[146:149], v[114:117]
	v_mfma_f32_16x16x32_bf16 v[106:109], v[238:241], v[146:149], v[106:109]
	v_mfma_f32_16x16x32_bf16 v[98:101], v[230:233], v[154:157], v[98:101]
	v_mfma_f32_16x16x32_bf16 v[90:93], v[238:241], v[154:157], v[90:93]
	v_mfma_f32_16x16x32_bf16 v[82:85], v[230:233], v[194:197], v[82:85]
	v_mfma_f32_16x16x32_bf16 v[74:77], v[238:241], v[194:197], v[74:77]
	v_mfma_f32_16x16x32_bf16 v[70:73], v[230:233], v[202:205], v[70:73]
	v_mfma_f32_16x16x32_bf16 v[66:69], v[238:241], v[202:205], v[66:69]
	v_mfma_f32_16x16x32_bf16 v[114:117], v[234:237], v[150:153], v[114:117]
	v_mfma_f32_16x16x32_bf16 v[106:109], v[242:245], v[150:153], v[106:109]
	v_mfma_f32_16x16x32_bf16 v[98:101], v[234:237], v[158:161], v[98:101]
	v_mfma_f32_16x16x32_bf16 v[90:93], v[242:245], v[158:161], v[90:93]
	v_mfma_f32_16x16x32_bf16 v[82:85], v[234:237], v[198:201], v[82:85]
	v_mfma_f32_16x16x32_bf16 v[74:77], v[242:245], v[198:201], v[74:77]
	v_mfma_f32_16x16x32_bf16 v[70:73], v[234:237], v[206:209], v[70:73]
	v_mfma_f32_16x16x32_bf16 v[66:69], v[242:245], v[206:209], v[66:69]
	s_setprio 0
	s_barrier
	ds_read_b128 v[146:149], v219 offset:16384
	ds_read_b128 v[150:153], v219 offset:17408
	ds_read_b128 v[154:157], v219 offset:18432
	ds_read_b128 v[158:161], v219 offset:19456
	ds_read_b128 v[194:197], v219 offset:20480
	ds_read_b128 v[198:201], v219 offset:21504
	ds_read_b128 v[202:205], v219 offset:22528
	ds_read_b128 v[206:209], v219 offset:23552
	s_cbranch_vccz .Lss_proj0
	v_lshlrev_b32_e32 v176, 4, v167
	s_lshl_b32 m0, s16, 1
	v_add_u32_e32 v176, s16, v176
	s_add_i32 m0, m0, 0x20000
	s_mov_b64 vcc, 0
	global_load_lds_dwordx4 v176, s[98:99]
	global_load_lds_dwordx4 v176, s[98:99] offset:1024
.Lss_proj0:
	s_add_i32 s22, s23, s4
	v_lshl_add_u64 v[176:177], s[30:31], 0, v[0:1]
	s_mov_b32 m0, s22
	s_nop 0
	global_load_lds_dwordx4 v[176:177], off
	v_lshl_add_u64 v[220:221], s[30:31], 0, v[178:179]
	s_add_i32 m0, s22, 0x2000
	s_nop 0
	global_load_lds_dwordx4 v[220:221], off
	s_mov_b32 m0, s16
	v_lshl_add_u64 v[246:247], s[44:45], 0, v[182:183]
	global_load_lds_dwordx4 v[246:247], off
	v_lshl_add_u64 v[248:249], s[44:45], 0, v[180:181]
	s_mov_b32 m0, s17
	s_nop 0
	global_load_lds_dwordx4 v[248:249], off
	s_add_u32 s22, s30, 0x40000
	s_addc_u32 s23, s31, 0
	s_add_i32 s1, s1, s4
	s_mov_b32 m0, s1
	s_nop 0
	global_load_lds_dwordx4 v0, s[22:23]
	s_add_i32 m0, s1, 0x2000
	s_nop 0
	global_load_lds_dwordx4 v178, s[22:23]
	s_waitcnt vmcnt(8)
	s_waitcnt lgkmcnt(0)
	s_barrier
	s_setprio 1
	v_mfma_f32_16x16x32_bf16 v[62:65], v[130:133], v[146:149], v[62:65]
	v_mfma_f32_16x16x32_bf16 v[58:61], v[138:141], v[146:149], v[58:61]
	v_mfma_f32_16x16x32_bf16 v[54:57], v[130:133], v[154:157], v[54:57]
	v_mfma_f32_16x16x32_bf16 v[46:49], v[138:141], v[154:157], v[46:49]
	v_mfma_f32_16x16x32_bf16 v[38:41], v[130:133], v[194:197], v[38:41]
	v_mfma_f32_16x16x32_bf16 v[30:33], v[138:141], v[194:197], v[30:33]
	v_mfma_f32_16x16x32_bf16 v[22:25], v[130:133], v[202:205], v[22:25]
	v_mfma_f32_16x16x32_bf16 v[14:17], v[138:141], v[202:205], v[14:17]
	v_mfma_f32_16x16x32_bf16 v[62:65], v[134:137], v[150:153], v[62:65]
	v_mfma_f32_16x16x32_bf16 v[58:61], v[142:145], v[150:153], v[58:61]
	v_mfma_f32_16x16x32_bf16 v[54:57], v[134:137], v[158:161], v[54:57]
	v_mfma_f32_16x16x32_bf16 v[46:49], v[142:145], v[158:161], v[46:49]
	v_mfma_f32_16x16x32_bf16 v[38:41], v[134:137], v[198:201], v[38:41]
	v_mfma_f32_16x16x32_bf16 v[30:33], v[142:145], v[198:201], v[30:33]
	v_mfma_f32_16x16x32_bf16 v[22:25], v[134:137], v[206:209], v[22:25]
	v_mfma_f32_16x16x32_bf16 v[14:17], v[142:145], v[206:209], v[14:17]
	v_mfma_f32_16x16x32_bf16 v[50:53], v[230:233], v[146:149], v[50:53]
	v_mfma_f32_16x16x32_bf16 v[42:45], v[238:241], v[146:149], v[42:45]
	v_mfma_f32_16x16x32_bf16 v[34:37], v[230:233], v[154:157], v[34:37]
	v_mfma_f32_16x16x32_bf16 v[26:29], v[238:241], v[154:157], v[26:29]
	v_mfma_f32_16x16x32_bf16 v[18:21], v[230:233], v[194:197], v[18:21]
	v_mfma_f32_16x16x32_bf16 v[10:13], v[238:241], v[194:197], v[10:13]
	v_mfma_f32_16x16x32_bf16 v[6:9], v[230:233], v[202:205], v[6:9]
	v_mfma_f32_16x16x32_bf16 v[2:5], v[238:241], v[202:205], v[2:5]
	v_mfma_f32_16x16x32_bf16 v[50:53], v[234:237], v[150:153], v[50:53]
	v_mfma_f32_16x16x32_bf16 v[42:45], v[242:245], v[150:153], v[42:45]
	v_mfma_f32_16x16x32_bf16 v[34:37], v[234:237], v[158:161], v[34:37]
	v_mfma_f32_16x16x32_bf16 v[26:29], v[242:245], v[158:161], v[26:29]
	v_mfma_f32_16x16x32_bf16 v[18:21], v[234:237], v[198:201], v[18:21]
	v_mfma_f32_16x16x32_bf16 v[10:13], v[242:245], v[198:201], v[10:13]
	v_mfma_f32_16x16x32_bf16 v[6:9], v[234:237], v[206:209], v[6:9]
	v_mfma_f32_16x16x32_bf16 v[2:5], v[242:245], v[206:209], v[2:5]
	s_setprio 0
	s_barrier
	s_add_i32 s1, 0, 0x18000
	v_add_u32_e32 v142, s1, v217
	ds_read_b128 v[130:133], v142
	ds_read_b128 v[134:137], v142 offset:1024
	ds_read_b128 v[138:141], v142 offset:2048
	ds_read_b128 v[142:145], v142 offset:3072
	s_add_u32 s22, s44, 0x40000
	s_addc_u32 s23, s45, 0
	s_mov_b32 m0, s20
	v_lshl_add_u64 v[230:231], s[22:23], 0, v[182:183]
	ds_read_b128 v[146:149], v219 offset:32768
	ds_read_b128 v[150:153], v219 offset:33792
	ds_read_b128 v[154:157], v219 offset:34816
	ds_read_b128 v[158:161], v219 offset:35840
	ds_read_b128 v[194:197], v219 offset:36864
	ds_read_b128 v[198:201], v219 offset:37888
	ds_read_b128 v[202:205], v219 offset:38912
	ds_read_b128 v[206:209], v219 offset:39936
	global_load_lds_dwordx4 v[230:231], off
	v_lshl_add_u64 v[230:231], s[22:23], 0, v[180:181]
	s_mov_b32 m0, s21
	s_nop 0
	global_load_lds_dwordx4 v[230:231], off
	s_add_i32 s33, 0, 0x1c000
	v_add_u32_e32 v168, s33, v217
	ds_read_b128 v[230:233], v168
	ds_read_b128 v[234:237], v168 offset:1024
	ds_read_b128 v[238:241], v168 offset:2048
	ds_read_b128 v[242:245], v168 offset:3072
	s_waitcnt vmcnt(8)
	s_waitcnt lgkmcnt(0)
	s_barrier
	s_setprio 1
	v_mfma_f32_16x16x32_bf16 v[126:129], v[130:133], v[146:149], v[126:129]
	v_mfma_f32_16x16x32_bf16 v[122:125], v[138:141], v[146:149], v[122:125]
	v_mfma_f32_16x16x32_bf16 v[118:121], v[130:133], v[154:157], v[118:121]
	v_mfma_f32_16x16x32_bf16 v[110:113], v[138:141], v[154:157], v[110:113]
	v_mfma_f32_16x16x32_bf16 v[102:105], v[130:133], v[194:197], v[102:105]
	v_mfma_f32_16x16x32_bf16 v[94:97], v[138:141], v[194:197], v[94:97]
	v_mfma_f32_16x16x32_bf16 v[86:89], v[130:133], v[202:205], v[86:89]
	v_mfma_f32_16x16x32_bf16 v[78:81], v[138:141], v[202:205], v[78:81]
	v_mfma_f32_16x16x32_bf16 v[126:129], v[134:137], v[150:153], v[126:129]
	v_mfma_f32_16x16x32_bf16 v[122:125], v[142:145], v[150:153], v[122:125]
	v_mfma_f32_16x16x32_bf16 v[118:121], v[134:137], v[158:161], v[118:121]
	v_mfma_f32_16x16x32_bf16 v[110:113], v[142:145], v[158:161], v[110:113]
	v_mfma_f32_16x16x32_bf16 v[102:105], v[134:137], v[198:201], v[102:105]
	v_mfma_f32_16x16x32_bf16 v[94:97], v[142:145], v[198:201], v[94:97]
	v_mfma_f32_16x16x32_bf16 v[86:89], v[134:137], v[206:209], v[86:89]
	v_mfma_f32_16x16x32_bf16 v[78:81], v[142:145], v[206:209], v[78:81]
	v_mfma_f32_16x16x32_bf16 v[114:117], v[230:233], v[146:149], v[114:117]
	v_mfma_f32_16x16x32_bf16 v[106:109], v[238:241], v[146:149], v[106:109]
	v_mfma_f32_16x16x32_bf16 v[98:101], v[230:233], v[154:157], v[98:101]
	v_mfma_f32_16x16x32_bf16 v[90:93], v[238:241], v[154:157], v[90:93]
	v_mfma_f32_16x16x32_bf16 v[82:85], v[230:233], v[194:197], v[82:85]
	v_mfma_f32_16x16x32_bf16 v[74:77], v[238:241], v[194:197], v[74:77]
	v_mfma_f32_16x16x32_bf16 v[70:73], v[230:233], v[202:205], v[70:73]
	v_mfma_f32_16x16x32_bf16 v[66:69], v[238:241], v[202:205], v[66:69]
	v_mfma_f32_16x16x32_bf16 v[114:117], v[234:237], v[150:153], v[114:117]
	v_mfma_f32_16x16x32_bf16 v[106:109], v[242:245], v[150:153], v[106:109]
	v_mfma_f32_16x16x32_bf16 v[98:101], v[234:237], v[158:161], v[98:101]
	v_mfma_f32_16x16x32_bf16 v[90:93], v[242:245], v[158:161], v[90:93]
	v_mfma_f32_16x16x32_bf16 v[82:85], v[234:237], v[198:201], v[82:85]
	v_mfma_f32_16x16x32_bf16 v[74:77], v[242:245], v[198:201], v[74:77]
	v_mfma_f32_16x16x32_bf16 v[70:73], v[234:237], v[206:209], v[70:73]
	v_mfma_f32_16x16x32_bf16 v[66:69], v[242:245], v[206:209], v[66:69]
	s_setprio 0
	s_barrier
	ds_read_b128 v[146:149], v219 offset:49152
	ds_read_b128 v[150:153], v219 offset:50176
	ds_read_b128 v[154:157], v219 offset:51200
	ds_read_b128 v[158:161], v219 offset:52224
	ds_read_b128 v[194:197], v219 offset:53248
	ds_read_b128 v[198:201], v219 offset:54272
	ds_read_b128 v[202:205], v219 offset:55296
	ds_read_b128 v[206:209], v219 offset:56320
	s_add_i32 s1, s1, s4
	v_lshl_add_u64 v[176:177], v[176:177], 0, s[12:13]
	s_mov_b32 m0, s1
	s_nop 0
	global_load_lds_dwordx4 v[176:177], off
	v_lshl_add_u64 v[176:177], v[220:221], 0, s[12:13]
	s_add_i32 m0, s1, 0x2000
	s_nop 0
	global_load_lds_dwordx4 v[176:177], off
	s_mov_b32 m0, s34
	v_lshl_add_u64 v[176:177], v[246:247], 0, s[12:13]
	global_load_lds_dwordx4 v[176:177], off
	v_lshl_add_u64 v[176:177], v[248:249], 0, s[12:13]
	s_mov_b32 m0, s46
	s_nop 0
	global_load_lds_dwordx4 v[176:177], off
	s_add_u32 s22, s30, 0x40080
	s_addc_u32 s23, s31, 0
	s_add_i32 s1, s33, s4
	s_mov_b32 m0, s1
	s_nop 0
	global_load_lds_dwordx4 v0, s[22:23]
	s_add_i32 m0, s1, 0x2000
	s_nop 0
	global_load_lds_dwordx4 v178, s[22:23]
	s_waitcnt vmcnt(8)
	s_waitcnt lgkmcnt(0)
	s_barrier
	s_setprio 1
	v_mfma_f32_16x16x32_bf16 v[62:65], v[130:133], v[146:149], v[62:65]
	v_mfma_f32_16x16x32_bf16 v[58:61], v[138:141], v[146:149], v[58:61]
	v_mfma_f32_16x16x32_bf16 v[54:57], v[130:133], v[154:157], v[54:57]
	v_mfma_f32_16x16x32_bf16 v[46:49], v[138:141], v[154:157], v[46:49]
	v_mfma_f32_16x16x32_bf16 v[38:41], v[130:133], v[194:197], v[38:41]
	v_mfma_f32_16x16x32_bf16 v[30:33], v[138:141], v[194:197], v[30:33]
	v_mfma_f32_16x16x32_bf16 v[22:25], v[130:133], v[202:205], v[22:25]
	v_mfma_f32_16x16x32_bf16 v[14:17], v[138:141], v[202:205], v[14:17]
	v_mfma_f32_16x16x32_bf16 v[62:65], v[134:137], v[150:153], v[62:65]
	v_mfma_f32_16x16x32_bf16 v[58:61], v[142:145], v[150:153], v[58:61]
	v_mfma_f32_16x16x32_bf16 v[54:57], v[134:137], v[158:161], v[54:57]
	v_mfma_f32_16x16x32_bf16 v[46:49], v[142:145], v[158:161], v[46:49]
	v_mfma_f32_16x16x32_bf16 v[38:41], v[134:137], v[198:201], v[38:41]
	v_mfma_f32_16x16x32_bf16 v[30:33], v[142:145], v[198:201], v[30:33]
	v_mfma_f32_16x16x32_bf16 v[22:25], v[134:137], v[206:209], v[22:25]
	v_mfma_f32_16x16x32_bf16 v[14:17], v[142:145], v[206:209], v[14:17]
	v_mfma_f32_16x16x32_bf16 v[50:53], v[230:233], v[146:149], v[50:53]
	v_mfma_f32_16x16x32_bf16 v[42:45], v[238:241], v[146:149], v[42:45]
	v_mfma_f32_16x16x32_bf16 v[34:37], v[230:233], v[154:157], v[34:37]
	v_mfma_f32_16x16x32_bf16 v[26:29], v[238:241], v[154:157], v[26:29]
	v_mfma_f32_16x16x32_bf16 v[18:21], v[230:233], v[194:197], v[18:21]
	v_mfma_f32_16x16x32_bf16 v[10:13], v[238:241], v[194:197], v[10:13]
	v_mfma_f32_16x16x32_bf16 v[6:9], v[230:233], v[202:205], v[6:9]
	v_mfma_f32_16x16x32_bf16 v[2:5], v[238:241], v[202:205], v[2:5]
	v_mfma_f32_16x16x32_bf16 v[50:53], v[234:237], v[150:153], v[50:53]
	v_mfma_f32_16x16x32_bf16 v[42:45], v[242:245], v[150:153], v[42:45]
	v_mfma_f32_16x16x32_bf16 v[34:37], v[234:237], v[158:161], v[34:37]
	v_mfma_f32_16x16x32_bf16 v[26:29], v[242:245], v[158:161], v[26:29]
	v_mfma_f32_16x16x32_bf16 v[18:21], v[234:237], v[198:201], v[18:21]
	v_mfma_f32_16x16x32_bf16 v[10:13], v[242:245], v[198:201], v[10:13]
	v_mfma_f32_16x16x32_bf16 v[6:9], v[234:237], v[206:209], v[6:9]
	v_mfma_f32_16x16x32_bf16 v[2:5], v[242:245], v[206:209], v[2:5]
	s_setprio 0
	s_add_i32 s54, s54, 2
	s_add_u32 s42, s42, 0x100
	s_addc_u32 s43, s43, 0
	s_add_u32 s52, s52, 0x100
	s_addc_u32 s53, s53, 0
	s_cmp_gt_u32 s54, 13
	s_barrier
	s_cbranch_scc0 .LBB0_289
	s_cmpk_gt_u32 s0, 0xff
	s_cbranch_scc1 .Lrs_proj0_post
	s_barrier
.Lrs_proj0_post:
	v_and_b32_e32 v250, 48, v212
	v_lshl_add_u32 v250, v216, 6, v250
	v_add_u32_e32 v250, 0x20000, v250
	v_lshl_add_u32 v208, s49, 8, v216
	v_ashrrev_i32_e32 v209, 31, v208
	v_lshlrev_b64 v[130:131], 6, v[208:209]
	v_or_b32_e32 v206, 16, v208
	v_lshl_add_u64 v[130:131], v[186:187], 0, v[130:131]
	v_ashrrev_i32_e32 v207, 31, v206
	ds_read_b128 v[154:157], v250
	v_lshlrev_b64 v[130:131], 6, v[206:207]
	v_lshl_add_u64 v[130:131], v[186:187], 0, v[130:131]
	ds_read_b128 v[158:161], v250 offset:1024
	v_or_b32_e32 v204, 32, v208
	v_ashrrev_i32_e32 v205, 31, v204
	v_lshlrev_b64 v[130:131], 6, v[204:205]
	v_or_b32_e32 v202, 48, v208
	v_lshl_add_u64 v[130:131], v[186:187], 0, v[130:131]
	v_ashrrev_i32_e32 v203, 31, v202
	ds_read_b128 v[150:153], v250 offset:2048
	v_lshlrev_b64 v[130:131], 6, v[202:203]
	v_lshl_add_u64 v[130:131], v[186:187], 0, v[130:131]
	ds_read_b128 v[146:149], v250 offset:3072
	v_add_u32_e32 v200, 0x80, v208
	v_ashrrev_i32_e32 v201, 31, v200
	v_lshlrev_b64 v[130:131], 6, v[200:201]
	v_add_u32_e32 v198, 0x90, v208
	v_lshl_add_u64 v[130:131], v[186:187], 0, v[130:131]
	v_ashrrev_i32_e32 v199, 31, v198
	ds_read_b128 v[142:145], v250 offset:8192
	v_lshlrev_b64 v[130:131], 6, v[198:199]
	v_add_u32_e32 v196, 0xa0, v208
	v_lshl_add_u64 v[130:131], v[186:187], 0, v[130:131]
	v_ashrrev_i32_e32 v197, 31, v196
	ds_read_b128 v[138:141], v250 offset:9216
	v_lshlrev_b64 v[130:131], 6, v[196:197]
	v_add_u32_e32 v194, 0xb0, v208
	v_lshl_add_u64 v[130:131], v[186:187], 0, v[130:131]
	v_ashrrev_i32_e32 v195, 31, v194
	ds_read_b128 v[134:137], v250 offset:10240
	v_lshlrev_b64 v[130:131], 6, v[194:195]
	v_lshl_add_u64 v[130:131], v[186:187], 0, v[130:131]
	ds_read_b128 v[130:133], v250 offset:11264
	v_and_b32_e32 v169, 64, v212
	v_xor_b32_e32 v168, 16, v212
	v_add_u32_e32 v169, 64, v169
	v_cmp_lt_i32_e32 vcc, v168, v169
	s_mov_b32 s22, 0x358637bd
	s_cmp_gt_i32 s48, 11
	v_cndmask_b32_e32 v168, v212, v168, vcc
	v_lshlrev_b32_e32 v221, 2, v168
	v_xor_b32_e32 v168, 32, v212
	v_cmp_lt_i32_e32 vcc, v168, v169
	s_cselect_b64 s[30:31], -1, 0
	v_readlane_b32 s50, v254, 42
	v_cndmask_b32_e32 v168, v212, v168, vcc
	v_lshlrev_b32_e32 v220, 2, v168
	s_mov_b64 s[44:45], -1
	s_movk_i32 s1, 0x1800
	s_movk_i32 s33, 0x7fff
	v_readlane_b32 s51, v254, 43
	s_waitcnt lgkmcnt(0)
	v_mov_b32_e32 v176, v155
	v_mov_b32_e32 v177, v156
	v_mov_b32_e32 v155, v157
	v_mov_b32_e32 v156, v159
	v_mov_b32_e32 v157, v160
	v_mov_b32_e32 v159, v161
	v_pk_add_f32 v[154:155], v[176:177], v[154:155]
	v_pk_add_f32 v[156:157], v[156:157], v[158:159]
	v_mov_b32_e32 v159, v154
	v_mov_b32_e32 v158, v156
	v_mov_b32_e32 v154, v157
	v_pk_add_f32 v[154:155], v[158:159], v[154:155]
	ds_bpermute_b32 v157, v221, v155
	ds_bpermute_b32 v156, v221, v154
	v_mov_b32_e32 v160, v151
	v_mov_b32_e32 v161, v152
	v_mov_b32_e32 v151, v153
	v_mov_b32_e32 v152, v147
	v_mov_b32_e32 v153, v148
	v_mov_b32_e32 v147, v149
	v_pk_add_f32 v[150:151], v[160:161], v[150:151]
	v_pk_add_f32 v[146:147], v[152:153], v[146:147]
	s_waitcnt lgkmcnt(0)
	v_pk_add_f32 v[154:155], v[154:155], v[156:157]
	v_mov_b32_e32 v148, v146
	v_mov_b32_e32 v149, v150
	v_mov_b32_e32 v150, v147
	ds_bpermute_b32 v157, v220, v155
	ds_bpermute_b32 v156, v220, v154
	v_pk_add_f32 v[146:147], v[148:149], v[150:151]
	ds_bpermute_b32 v149, v221, v147
	ds_bpermute_b32 v148, v221, v146
	v_mov_b64_e32 v[158:159], s[22:23]
	s_waitcnt lgkmcnt(2)
	v_pk_add_f32 v[154:155], v[154:155], v[156:157]
	s_mov_b32 s22, 0x3a800000
	v_pk_fma_f32 v[154:155], v[154:155], s[22:23], v[158:159] op_sel_hi:[1,0,0]
	s_waitcnt lgkmcnt(0)
	v_pk_add_f32 v[146:147], v[146:147], v[148:149]
	v_mul_f32_e32 v156, 0x4b800000, v155
	v_cmp_gt_f32_e64 s[42:43], s39, v155
	ds_bpermute_b32 v149, v220, v147
	ds_bpermute_b32 v148, v220, v146
	v_cndmask_b32_e64 v155, v155, v156, s[42:43]
	v_rsq_f32_e32 v155, v155
	v_mov_b32_e32 v150, v143
	v_mov_b32_e32 v151, v144
	v_mov_b32_e32 v143, v145
	v_mov_b32_e32 v144, v139
	v_mov_b32_e32 v145, v140
	v_mov_b32_e32 v139, v141
	s_waitcnt lgkmcnt(0)
	v_pk_add_f32 v[146:147], v[146:147], v[148:149]
	v_pk_add_f32 v[142:143], v[150:151], v[142:143]
	v_pk_add_f32 v[138:139], v[144:145], v[138:139]
	v_mul_f32_e32 v156, 0x45800000, v155
	v_pk_fma_f32 v[148:149], v[146:147], s[22:23], v[158:159] op_sel_hi:[1,0,0]
	v_mov_b32_e32 v140, v138
	v_mov_b32_e32 v141, v142
	v_mov_b32_e32 v142, v139
	v_cmp_gt_f32_e32 vcc, s39, v154
	v_cndmask_b32_e64 v156, v155, v156, s[42:43]
	v_mul_f32_e32 v155, 0x4b800000, v154
	v_mul_f32_e32 v146, 0x4b800000, v149
	v_cmp_gt_f32_e64 s[42:43], s39, v149
	v_pk_add_f32 v[138:139], v[140:141], v[142:143]
	v_mov_b32_e32 v142, v135
	v_mov_b32_e32 v143, v136
	v_mov_b32_e32 v135, v137
	v_mov_b32_e32 v136, v131
	v_mov_b32_e32 v137, v132
	v_mov_b32_e32 v131, v133
	v_cndmask_b32_e32 v154, v154, v155, vcc
	v_cndmask_b32_e64 v146, v149, v146, s[42:43]
	v_pk_add_f32 v[134:135], v[142:143], v[134:135]
	v_pk_add_f32 v[130:131], v[136:137], v[130:131]
	v_rsq_f32_e32 v154, v154
	v_rsq_f32_e32 v146, v146
	v_mov_b32_e32 v132, v130
	v_mov_b32_e32 v133, v134
	v_mov_b32_e32 v134, v131
	v_pk_add_f32 v[130:131], v[132:133], v[134:135]
	ds_bpermute_b32 v141, v221, v139
	ds_bpermute_b32 v140, v221, v138
	ds_bpermute_b32 v133, v221, v131
	ds_bpermute_b32 v132, v221, v130
	v_mul_f32_e32 v155, 0x45800000, v154
	v_mul_f32_e32 v147, 0x45800000, v146
	v_cndmask_b32_e32 v154, v154, v155, vcc
	v_cmp_gt_f32_e32 vcc, s39, v148
	v_cndmask_b32_e64 v146, v146, v147, s[42:43]
	v_mul_f32_e32 v147, 0x4b800000, v148
	v_cndmask_b32_e32 v147, v148, v147, vcc
	v_rsq_f32_e32 v147, v147
	s_waitcnt lgkmcnt(2)
	v_pk_add_f32 v[138:139], v[138:139], v[140:141]
	s_waitcnt lgkmcnt(0)
	v_pk_add_f32 v[132:133], v[130:131], v[132:133]
	ds_bpermute_b32 v141, v220, v139
	ds_bpermute_b32 v140, v220, v138
	ds_bpermute_b32 v135, v220, v133
	ds_bpermute_b32 v134, v220, v132
	v_mul_f32_e32 v148, 0x45800000, v147
	v_cndmask_b32_e64 v130, 0, 1, s[24:25]
	v_cndmask_b32_e32 v148, v147, v148, vcc
	s_and_b64 vcc, exec, s[30:31]
	v_cmp_ne_u32_e64 s[42:43], 1, v130
	s_cbranch_vccz .LBB0_294
	s_and_b64 vcc, exec, s[42:43]
	s_cbranch_vccnz .LBB0_293
	global_load_dwordx4 v[142:145], v[188:189], off
	v_lshlrev_b64 v[130:131], 7, v[208:209]
	v_lshl_add_u64 v[130:131], v[184:185], 0, v[130:131]
	s_waitcnt vmcnt(0)
	v_pk_fma_f32 v[144:145], v[128:129], v[156:157], v[144:145] op_sel_hi:[1,0,1]
	v_pk_fma_f32 v[142:143], v[126:127], v[156:157], v[142:143] op_sel_hi:[1,0,1]
	global_store_dwordx4 v[130:131], v[142:145], off
	global_load_dwordx4 v[142:145], v[188:189], off offset:16
	s_waitcnt vmcnt(0)
	v_pk_fma_f32 v[144:145], v[124:125], v[156:157], v[144:145] op_sel_hi:[1,0,1]
	v_pk_fma_f32 v[142:143], v[122:123], v[156:157], v[142:143] op_sel_hi:[1,0,1]
	global_store_dwordx4 v[130:131], v[142:145], off offset:16
	global_load_dwordx4 v[142:145], v[188:189], off
	v_lshlrev_b64 v[130:131], 7, v[206:207]
	v_lshl_add_u64 v[130:131], v[184:185], 0, v[130:131]
	s_waitcnt vmcnt(0)
	v_pk_fma_f32 v[144:145], v[120:121], v[154:155], v[144:145] op_sel_hi:[1,0,1]
	v_pk_fma_f32 v[142:143], v[118:119], v[154:155], v[142:143] op_sel_hi:[1,0,1]
	global_store_dwordx4 v[130:131], v[142:145], off
	global_load_dwordx4 v[142:145], v[188:189], off offset:16
	s_waitcnt vmcnt(0)
	v_pk_fma_f32 v[144:145], v[112:113], v[154:155], v[144:145] op_sel_hi:[1,0,1]
	v_pk_fma_f32 v[142:143], v[110:111], v[154:155], v[142:143] op_sel_hi:[1,0,1]
	global_store_dwordx4 v[130:131], v[142:145], off offset:16
	global_load_dwordx4 v[142:145], v[188:189], off
	v_lshlrev_b64 v[130:131], 7, v[204:205]
	v_lshl_add_u64 v[130:131], v[184:185], 0, v[130:131]
	s_waitcnt vmcnt(0)
	v_pk_fma_f32 v[144:145], v[104:105], v[146:147], v[144:145] op_sel_hi:[1,0,1]
	v_pk_fma_f32 v[142:143], v[102:103], v[146:147], v[142:143] op_sel_hi:[1,0,1]
	global_store_dwordx4 v[130:131], v[142:145], off
	global_load_dwordx4 v[142:145], v[188:189], off offset:16
	s_waitcnt vmcnt(0)
	v_pk_fma_f32 v[144:145], v[96:97], v[146:147], v[144:145] op_sel_hi:[1,0,1]
	v_pk_fma_f32 v[142:143], v[94:95], v[146:147], v[142:143] op_sel_hi:[1,0,1]
	global_store_dwordx4 v[130:131], v[142:145], off offset:16
	global_load_dwordx4 v[142:145], v[188:189], off
	v_lshlrev_b64 v[130:131], 7, v[202:203]
	v_lshl_add_u64 v[130:131], v[184:185], 0, v[130:131]
	s_waitcnt vmcnt(0)
	v_pk_fma_f32 v[144:145], v[88:89], v[148:149], v[144:145] op_sel_hi:[1,0,1]
	v_pk_fma_f32 v[142:143], v[86:87], v[148:149], v[142:143] op_sel_hi:[1,0,1]
	global_store_dwordx4 v[130:131], v[142:145], off
	global_load_dwordx4 v[142:145], v[188:189], off offset:16
	s_waitcnt vmcnt(0)
	v_pk_fma_f32 v[144:145], v[80:81], v[148:149], v[144:145] op_sel_hi:[1,0,1]
	v_pk_fma_f32 v[142:143], v[78:79], v[148:149], v[142:143] op_sel_hi:[1,0,1]
	global_store_dwordx4 v[130:131], v[142:145], off offset:16

.LBB0_357:
	v_bfe_u32 v18, v16, 4, 2
	s_and_b64 s[6:7], s[6:7], exec
	v_and_b32_e32 v17, 15, v16
	v_lshlrev_b32_e32 v19, 3, v18
	v_lshlrev_b32_e32 v18, 4, v18
	v_lshlrev_b32_e32 v16, 2, v16
	s_cselect_b32 s54, 0, 0x4000
	s_and_b32 s6, s8, 3
	v_lshl_or_b32 v159, s0, 6, v17
	v_lshl_or_b32 v17, v17, 6, v18
	s_lshl_b32 s0, s0, 13
	v_and_b32_e32 v16, 32, v16
	s_add_i32 m0, s49, 0x18000
	v_lshl_add_u64 v[8:9], v[8:9], 0, s[12:13]
	v_bitop3_b32 v20, v17, s0, v16 bitop3:0xde
	s_lshl_b32 s0, s6, 12
	s_waitcnt vmcnt(2)
	s_barrier
	global_load_lds_dwordx4 v[8:9], off
	v_lshl_add_u64 v[6:7], v[6:7], 0, s[12:13]
	s_add_i32 m0, s49, 0x1a000
	s_add_i32 s55, s49, 0x8000
	s_add_i32 s56, s49, 0xa000
	v_bitop3_b32 v181, v17, s0, v16 bitop3:0xde
	global_load_lds_dwordx4 v[6:7], off
	v_lshl_add_u64 v[4:5], v[4:5], 0, s[12:13]
	s_mov_b32 m0, s55
	s_add_u32 s0, s30, 0x40080
	global_load_lds_dwordx4 v[4:5], off
	v_lshl_add_u64 v[2:3], v[2:3], 0, s[12:13]
	s_mov_b32 m0, s56
	s_addc_u32 s1, s31, 0
	global_load_lds_dwordx4 v[2:3], off
	s_add_i32 m0, s49, 0x1c000
	v_lshl_add_u64 v[2:3], s[0:1], 0, v[0:1]
	global_load_lds_dwordx4 v[2:3], off
	v_lshl_add_u64 v[2:3], s[0:1], 0, v[138:139]
	s_add_i32 m0, s49, 0x1e000
	v_readlane_b32 s0, v254, 39
	global_load_lds_dwordx4 v[2:3], off
	v_lshlrev_b32_e32 v2, 14, v14
	v_and_b32_e32 v2, 0xffff8000, v2
	v_lshl_add_u32 v2, v13, 11, v2
	v_and_b32_e32 v3, 1, v14
	v_lshl_or_b32 v183, s6, 5, v19
	v_mov_b32_e32 v19, v1
	v_readlane_b32 s1, v254, 40
	v_lshl_or_b32 v2, v3, 6, v2
	v_lshl_add_u32 v150, v15, 1, v2
	s_mov_b64 s[100:101], s[0:1]
	v_lshl_add_u64 v[144:145], s[0:1], 0, v[18:19]
	v_readlane_b32 s0, v254, 44
	v_lshlrev_b32_e32 v2, 14, v10
	v_readlane_b32 s1, v254, 45
	v_and_b32_e32 v2, 0xffff8000, v2
	s_waitcnt vmcnt(6)
	v_lshl_add_u32 v2, v11, 11, v2
	v_lshl_add_u64 v[146:147], s[0:1], 0, v[18:19]
	v_readlane_b32 s0, v254, 46
	v_and_b32_e32 v3, 1, v10
	s_cmp_eq_u32 s6, 0
	v_readlane_b32 s1, v254, 47
	v_lshl_or_b32 v2, v3, 6, v2
	v_readlane_b32 s8, v253, 31
	s_mov_b32 s53, 0
	s_cselect_b64 s[6:7], -1, 0
	v_lshl_add_u64 v[148:149], s[0:1], 0, v[18:19]
	v_mov_b32_e32 v151, v1
	v_lshl_add_u32 v152, v12, 1, v2
	v_mov_b32_e32 v153, v1
	v_add_u32_e32 v185, 0, v20
	v_readlane_b32 s0, v253, 23
	s_mov_b32 s16, s8
	s_movk_i32 s57, 0x121
	s_mov_b32 s58, 0x3a800000
	s_mov_b32 s60, 0x358637bd
	s_barrier
	v_readlane_b32 s9, v253, 32
	s_branch .LBB0_359

.LBB0_361:
	s_ashr_i32 s25, s24, 31
	s_lshl_b64 s[20:21], s[24:25], 19
	v_cmp_lt_i64_e32 vcc, s[26:27], v[174:175]
	s_add_u32 s26, s46, s20
	s_addc_u32 s27, s47, s21
	s_and_b64 s[20:21], vcc, exec
	s_cselect_b32 s17, s27, s29
	s_cselect_b32 s20, s26, s28
	s_ashr_i32 s9, s8, 31
	s_lshl_b64 s[22:23], s[8:9], 19
	v_readlane_b32 s36, v254, 42
	v_readlane_b32 s37, v254, 43
	s_add_u32 s36, s36, s22
	s_addc_u32 s37, s37, s23
	s_and_b64 s[22:23], vcc, exec
	s_cselect_b32 s9, s37, s31
	s_cselect_b32 s21, s36, s30
	s_add_u32 s28, s28, 0x40080
	s_addc_u32 s29, s29, 0
	s_add_u32 s25, s30, 0x100
	v_mov_b32_e32 v2, 0
	s_addc_u32 s34, s31, 0
	s_mov_b32 s44, -2
	v_mov_b32_e32 v3, v2
	v_mov_b32_e32 v4, v2
	v_mov_b32_e32 v5, v2
	v_mov_b32_e32 v6, v2
	v_mov_b32_e32 v7, v2
	v_mov_b32_e32 v8, v2
	v_mov_b32_e32 v9, v2
	v_mov_b32_e32 v18, v2
	v_mov_b32_e32 v19, v2
	v_mov_b32_e32 v20, v2
	v_mov_b32_e32 v21, v2
	v_mov_b32_e32 v22, v2
	v_mov_b32_e32 v23, v2
	v_mov_b32_e32 v24, v2
	v_mov_b32_e32 v25, v2
	v_mov_b32_e32 v34, v2
	v_mov_b32_e32 v35, v2
	v_mov_b32_e32 v36, v2
	v_mov_b32_e32 v37, v2
	v_mov_b32_e32 v38, v2
	v_mov_b32_e32 v39, v2
	v_mov_b32_e32 v40, v2
	v_mov_b32_e32 v41, v2
	v_mov_b32_e32 v50, v2
	v_mov_b32_e32 v51, v2
	v_mov_b32_e32 v52, v2
	v_mov_b32_e32 v53, v2
	v_mov_b32_e32 v54, v2
	v_mov_b32_e32 v55, v2
	v_mov_b32_e32 v56, v2
	v_mov_b32_e32 v57, v2
	v_mov_b32_e32 v10, v2
	v_mov_b32_e32 v11, v2
	v_mov_b32_e32 v12, v2
	v_mov_b32_e32 v13, v2
	v_mov_b32_e32 v14, v2
	v_mov_b32_e32 v15, v2
	v_mov_b32_e32 v16, v2
	v_mov_b32_e32 v17, v2
	v_mov_b32_e32 v26, v2
	v_mov_b32_e32 v27, v2
	v_mov_b32_e32 v28, v2
	v_mov_b32_e32 v29, v2
	v_mov_b32_e32 v30, v2
	v_mov_b32_e32 v31, v2
	v_mov_b32_e32 v32, v2
	v_mov_b32_e32 v33, v2
	v_mov_b32_e32 v42, v2
	v_mov_b32_e32 v43, v2
	v_mov_b32_e32 v44, v2
	v_mov_b32_e32 v45, v2
	v_mov_b32_e32 v46, v2
	v_mov_b32_e32 v47, v2
	v_mov_b32_e32 v48, v2
	v_mov_b32_e32 v49, v2
	v_mov_b32_e32 v58, v2
	v_mov_b32_e32 v59, v2
	v_mov_b32_e32 v60, v2
	v_mov_b32_e32 v61, v2
	v_mov_b32_e32 v62, v2
	v_mov_b32_e32 v63, v2
	v_mov_b32_e32 v64, v2
	v_mov_b32_e32 v65, v2
	v_mov_b32_e32 v66, v2
	v_mov_b32_e32 v67, v2
	v_mov_b32_e32 v68, v2
	v_mov_b32_e32 v69, v2
	v_mov_b32_e32 v70, v2
	v_mov_b32_e32 v71, v2
	v_mov_b32_e32 v72, v2
	v_mov_b32_e32 v73, v2
	v_mov_b32_e32 v82, v2
	v_mov_b32_e32 v83, v2
	v_mov_b32_e32 v84, v2
	v_mov_b32_e32 v85, v2
	v_mov_b32_e32 v86, v2
	v_mov_b32_e32 v87, v2
	v_mov_b32_e32 v88, v2
	v_mov_b32_e32 v89, v2
	v_mov_b32_e32 v98, v2
	v_mov_b32_e32 v99, v2
	v_mov_b32_e32 v100, v2
	v_mov_b32_e32 v101, v2
	v_mov_b32_e32 v102, v2
	v_mov_b32_e32 v103, v2
	v_mov_b32_e32 v104, v2
	v_mov_b32_e32 v105, v2
	v_mov_b32_e32 v114, v2
	v_mov_b32_e32 v115, v2
	v_mov_b32_e32 v116, v2
	v_mov_b32_e32 v117, v2
	v_mov_b32_e32 v118, v2
	v_mov_b32_e32 v119, v2
	v_mov_b32_e32 v120, v2
	v_mov_b32_e32 v121, v2
	v_mov_b32_e32 v74, v2
	v_mov_b32_e32 v75, v2
	v_mov_b32_e32 v76, v2
	v_mov_b32_e32 v77, v2
	v_mov_b32_e32 v78, v2
	v_mov_b32_e32 v79, v2
	v_mov_b32_e32 v80, v2
	v_mov_b32_e32 v81, v2
	v_mov_b32_e32 v90, v2
	v_mov_b32_e32 v91, v2
	v_mov_b32_e32 v92, v2
	v_mov_b32_e32 v93, v2
	v_mov_b32_e32 v94, v2
	v_mov_b32_e32 v95, v2
	v_mov_b32_e32 v96, v2
	v_mov_b32_e32 v97, v2
	v_mov_b32_e32 v106, v2
	v_mov_b32_e32 v107, v2
	v_mov_b32_e32 v108, v2
	v_mov_b32_e32 v109, v2
	v_mov_b32_e32 v110, v2
	v_mov_b32_e32 v111, v2
	v_mov_b32_e32 v112, v2
	v_mov_b32_e32 v113, v2
	v_mov_b32_e32 v122, v2
	v_mov_b32_e32 v123, v2
	v_mov_b32_e32 v124, v2
	v_mov_b32_e32 v125, v2
	v_mov_b32_e32 v126, v2
	v_mov_b32_e32 v127, v2
	v_mov_b32_e32 v128, v2
	v_mov_b32_e32 v129, v2
	s_lshl_b32 s98, s16, 8
	s_add_i32 s98, s98, s54
	s_lshl_b32 s98, s98, 6
	s_add_u32 s98, s100, s98
	s_addc_u32 s99, s101, 0
	s_mov_b64 vcc, -1
	s_cmpk_gt_u32 s4, 0xff
	s_cbranch_scc0 .Lrs_proj1_pre
	s_barrier
.Lrs_proj1_pre:
.LBB0_362:
	s_add_u32 s1, s28, 0xfffc0080
	s_addc_u32 s22, s29, -1
	s_add_i32 s23, 0, 0x10000
	v_add_u32_e32 v158, s23, v181
	ds_read_b128 v[130:133], v158
	ds_read_b128 v[134:137], v158 offset:1024
	ds_read_b128 v[154:157], v158 offset:2048
	ds_read_b128 v[186:189], v158 offset:3072
	s_cmp_eq_u32 s44, 12
	s_cselect_b32 s43, s17, s22
	s_cselect_b32 s42, s20, s1
	s_cselect_b32 s31, s9, s34
	s_cselect_b32 s30, s21, s25
	v_lshl_add_u64 v[160:161], s[28:29], 0, v[150:151]
	s_add_i32 m0, s49, 0xc000
	ds_read_b128 v[190:193], v185
	ds_read_b128 v[194:197], v185 offset:1024
	ds_read_b128 v[198:201], v185 offset:2048
	ds_read_b128 v[202:205], v185 offset:3072
	ds_read_b128 v[206:209], v185 offset:4096
	ds_read_b128 v[216:219], v185 offset:5120
	ds_read_b128 v[230:233], v185 offset:6144
	ds_read_b128 v[234:237], v185 offset:7168
	global_load_lds_dwordx4 v[160:161], off
	v_lshl_add_u64 v[160:161], s[28:29], 0, v[152:153]
	s_add_i32 m0, s49, 0xe000
	s_nop 0
	global_load_lds_dwordx4 v[160:161], off
	s_add_i32 s1, 0, 0x14000
	v_add_u32_e32 v158, s1, v181
	ds_read_b128 v[238:241], v158
	ds_read_b128 v[242:245], v158 offset:1024
	ds_read_b128 v[246:249], v158 offset:2048
	ds_read_b128 v[176:179], v158 offset:3072
	s_waitcnt vmcnt(8)
	s_waitcnt lgkmcnt(0)
	s_barrier
	s_setprio 1
	v_mfma_f32_16x16x32_bf16 v[126:129], v[130:133], v[190:193], v[126:129]
	v_mfma_f32_16x16x32_bf16 v[122:125], v[154:157], v[190:193], v[122:125]
	v_mfma_f32_16x16x32_bf16 v[110:113], v[130:133], v[198:201], v[110:113]
	v_mfma_f32_16x16x32_bf16 v[106:109], v[154:157], v[198:201], v[106:109]
	v_mfma_f32_16x16x32_bf16 v[94:97], v[130:133], v[206:209], v[94:97]
	v_mfma_f32_16x16x32_bf16 v[90:93], v[154:157], v[206:209], v[90:93]
	v_mfma_f32_16x16x32_bf16 v[78:81], v[130:133], v[230:233], v[78:81]
	v_mfma_f32_16x16x32_bf16 v[74:77], v[154:157], v[230:233], v[74:77]
	v_mfma_f32_16x16x32_bf16 v[126:129], v[134:137], v[194:197], v[126:129]
	v_mfma_f32_16x16x32_bf16 v[122:125], v[186:189], v[194:197], v[122:125]
	v_mfma_f32_16x16x32_bf16 v[110:113], v[134:137], v[202:205], v[110:113]
	v_mfma_f32_16x16x32_bf16 v[106:109], v[186:189], v[202:205], v[106:109]
	v_mfma_f32_16x16x32_bf16 v[94:97], v[134:137], v[216:219], v[94:97]
	v_mfma_f32_16x16x32_bf16 v[90:93], v[186:189], v[216:219], v[90:93]
	v_mfma_f32_16x16x32_bf16 v[78:81], v[134:137], v[234:237], v[78:81]
	v_mfma_f32_16x16x32_bf16 v[74:77], v[186:189], v[234:237], v[74:77]
	v_mfma_f32_16x16x32_bf16 v[118:121], v[238:241], v[190:193], v[118:121]
	v_mfma_f32_16x16x32_bf16 v[114:117], v[246:249], v[190:193], v[114:117]
	v_mfma_f32_16x16x32_bf16 v[102:105], v[238:241], v[198:201], v[102:105]
	v_mfma_f32_16x16x32_bf16 v[98:101], v[246:249], v[198:201], v[98:101]
	v_mfma_f32_16x16x32_bf16 v[86:89], v[238:241], v[206:209], v[86:89]
	v_mfma_f32_16x16x32_bf16 v[82:85], v[246:249], v[206:209], v[82:85]
	v_mfma_f32_16x16x32_bf16 v[70:73], v[238:241], v[230:233], v[70:73]
	v_mfma_f32_16x16x32_bf16 v[66:69], v[246:249], v[230:233], v[66:69]
	v_mfma_f32_16x16x32_bf16 v[118:121], v[242:245], v[194:197], v[118:121]
	v_mfma_f32_16x16x32_bf16 v[114:117], v[176:179], v[194:197], v[114:117]
	v_mfma_f32_16x16x32_bf16 v[102:105], v[242:245], v[202:205], v[102:105]
	v_mfma_f32_16x16x32_bf16 v[98:101], v[176:179], v[202:205], v[98:101]
	v_mfma_f32_16x16x32_bf16 v[86:89], v[242:245], v[216:219], v[86:89]
	v_mfma_f32_16x16x32_bf16 v[82:85], v[176:179], v[216:219], v[82:85]
	v_mfma_f32_16x16x32_bf16 v[70:73], v[242:245], v[234:237], v[70:73]
	v_mfma_f32_16x16x32_bf16 v[66:69], v[176:179], v[234:237], v[66:69]
	s_setprio 0
	s_barrier
	ds_read_b128 v[190:193], v185 offset:16384
	ds_read_b128 v[194:197], v185 offset:17408
	ds_read_b128 v[198:201], v185 offset:18432
	ds_read_b128 v[202:205], v185 offset:19456
	ds_read_b128 v[206:209], v185 offset:20480
	ds_read_b128 v[216:219], v185 offset:21504
	ds_read_b128 v[230:233], v185 offset:22528
	ds_read_b128 v[234:237], v185 offset:23552
	s_cbranch_vccz .Lss_proj1
	v_lshlrev_b32_e32 v160, 4, v167
	s_lshl_b32 m0, s49, 1
	v_add_u32_e32 v160, s49, v160
	s_add_i32 m0, m0, 0x20000
	s_mov_b64 vcc, 0
	global_load_lds_dwordx4 v160, s[98:99]
	global_load_lds_dwordx4 v160, s[98:99] offset:1024
.Lss_proj1:
	s_add_i32 s22, s23, s48
	v_lshl_add_u64 v[160:161], s[30:31], 0, v[0:1]
	s_mov_b32 m0, s22
	s_nop 0
	global_load_lds_dwordx4 v[160:161], off
	v_lshl_add_u64 v[220:221], s[30:31], 0, v[138:139]
	s_add_i32 m0, s22, 0x2000
	s_nop 0
	global_load_lds_dwordx4 v[220:221], off
	s_mov_b32 m0, s49
	v_lshl_add_u64 v[250:251], s[42:43], 0, v[142:143]
	global_load_lds_dwordx4 v[250:251], off
	v_lshl_add_u64 v[168:169], s[42:43], 0, v[140:141]
	s_mov_b32 m0, s50
	s_nop 0
	global_load_lds_dwordx4 v[168:169], off
	s_add_u32 s22, s30, 0x40000
	s_addc_u32 s23, s31, 0
	s_add_i32 s1, s1, s48
	s_mov_b32 m0, s1
	s_nop 0
	global_load_lds_dwordx4 v0, s[22:23]
	s_add_i32 m0, s1, 0x2000
	s_nop 0
	global_load_lds_dwordx4 v138, s[22:23]
	s_waitcnt vmcnt(8)
	s_waitcnt lgkmcnt(0)
	s_barrier
	s_setprio 1
	v_mfma_f32_16x16x32_bf16 v[62:65], v[130:133], v[190:193], v[62:65]
	v_mfma_f32_16x16x32_bf16 v[58:61], v[154:157], v[190:193], v[58:61]
	v_mfma_f32_16x16x32_bf16 v[46:49], v[130:133], v[198:201], v[46:49]
	v_mfma_f32_16x16x32_bf16 v[42:45], v[154:157], v[198:201], v[42:45]
	v_mfma_f32_16x16x32_bf16 v[30:33], v[130:133], v[206:209], v[30:33]
	v_mfma_f32_16x16x32_bf16 v[26:29], v[154:157], v[206:209], v[26:29]
	v_mfma_f32_16x16x32_bf16 v[14:17], v[130:133], v[230:233], v[14:17]
	v_mfma_f32_16x16x32_bf16 v[10:13], v[154:157], v[230:233], v[10:13]
	v_mfma_f32_16x16x32_bf16 v[62:65], v[134:137], v[194:197], v[62:65]
	v_mfma_f32_16x16x32_bf16 v[58:61], v[186:189], v[194:197], v[58:61]
	v_mfma_f32_16x16x32_bf16 v[46:49], v[134:137], v[202:205], v[46:49]
	v_mfma_f32_16x16x32_bf16 v[42:45], v[186:189], v[202:205], v[42:45]
	v_mfma_f32_16x16x32_bf16 v[30:33], v[134:137], v[216:219], v[30:33]
	v_mfma_f32_16x16x32_bf16 v[26:29], v[186:189], v[216:219], v[26:29]
	v_mfma_f32_16x16x32_bf16 v[14:17], v[134:137], v[234:237], v[14:17]
	v_mfma_f32_16x16x32_bf16 v[10:13], v[186:189], v[234:237], v[10:13]
	v_mfma_f32_16x16x32_bf16 v[54:57], v[238:241], v[190:193], v[54:57]
	v_mfma_f32_16x16x32_bf16 v[50:53], v[246:249], v[190:193], v[50:53]
	v_mfma_f32_16x16x32_bf16 v[38:41], v[238:241], v[198:201], v[38:41]
	v_mfma_f32_16x16x32_bf16 v[34:37], v[246:249], v[198:201], v[34:37]
	v_mfma_f32_16x16x32_bf16 v[22:25], v[238:241], v[206:209], v[22:25]
	v_mfma_f32_16x16x32_bf16 v[18:21], v[246:249], v[206:209], v[18:21]
	v_mfma_f32_16x16x32_bf16 v[6:9], v[238:241], v[230:233], v[6:9]
	v_mfma_f32_16x16x32_bf16 v[2:5], v[246:249], v[230:233], v[2:5]
	v_mfma_f32_16x16x32_bf16 v[54:57], v[242:245], v[194:197], v[54:57]
	v_mfma_f32_16x16x32_bf16 v[50:53], v[176:179], v[194:197], v[50:53]
	v_mfma_f32_16x16x32_bf16 v[38:41], v[242:245], v[202:205], v[38:41]
	v_mfma_f32_16x16x32_bf16 v[34:37], v[176:179], v[202:205], v[34:37]
	v_mfma_f32_16x16x32_bf16 v[22:25], v[242:245], v[216:219], v[22:25]
	v_mfma_f32_16x16x32_bf16 v[18:21], v[176:179], v[216:219], v[18:21]
	v_mfma_f32_16x16x32_bf16 v[6:9], v[242:245], v[234:237], v[6:9]
	v_mfma_f32_16x16x32_bf16 v[2:5], v[176:179], v[234:237], v[2:5]
	s_setprio 0
	s_barrier
	s_add_i32 s1, 0, 0x18000
	v_add_u32_e32 v158, s1, v181
	ds_read_b128 v[130:133], v158
	ds_read_b128 v[134:137], v158 offset:1024
	ds_read_b128 v[154:157], v158 offset:2048
	ds_read_b128 v[176:179], v158 offset:3072
	s_add_u32 s22, s42, 0x40000
	s_addc_u32 s23, s43, 0
	s_mov_b32 m0, s51
	v_lshl_add_u64 v[234:235], s[22:23], 0, v[142:143]
	ds_read_b128 v[186:189], v185 offset:32768
	ds_read_b128 v[190:193], v185 offset:33792
	ds_read_b128 v[194:197], v185 offset:34816
	ds_read_b128 v[198:201], v185 offset:35840
	ds_read_b128 v[202:205], v185 offset:36864
	ds_read_b128 v[206:209], v185 offset:37888
	ds_read_b128 v[216:219], v185 offset:38912
	ds_read_b128 v[230:233], v185 offset:39936
	global_load_lds_dwordx4 v[234:235], off
	v_lshl_add_u64 v[234:235], s[22:23], 0, v[140:141]
	s_mov_b32 m0, s52
	s_nop 0
	global_load_lds_dwordx4 v[234:235], off
	s_add_i32 s33, 0, 0x1c000
	v_add_u32_e32 v158, s33, v181
	ds_read_b128 v[234:237], v158
	ds_read_b128 v[238:241], v158 offset:1024
	ds_read_b128 v[242:245], v158 offset:2048
	ds_read_b128 v[246:249], v158 offset:3072
	s_waitcnt vmcnt(8)
	s_waitcnt lgkmcnt(0)
	s_barrier
	s_setprio 1
	v_mfma_f32_16x16x32_bf16 v[126:129], v[130:133], v[186:189], v[126:129]
	v_mfma_f32_16x16x32_bf16 v[122:125], v[154:157], v[186:189], v[122:125]
	v_mfma_f32_16x16x32_bf16 v[110:113], v[130:133], v[194:197], v[110:113]
	v_mfma_f32_16x16x32_bf16 v[106:109], v[154:157], v[194:197], v[106:109]
	v_mfma_f32_16x16x32_bf16 v[94:97], v[130:133], v[202:205], v[94:97]
	v_mfma_f32_16x16x32_bf16 v[90:93], v[154:157], v[202:205], v[90:93]
	v_mfma_f32_16x16x32_bf16 v[78:81], v[130:133], v[216:219], v[78:81]
	v_mfma_f32_16x16x32_bf16 v[74:77], v[154:157], v[216:219], v[74:77]
	v_mfma_f32_16x16x32_bf16 v[126:129], v[134:137], v[190:193], v[126:129]
	v_mfma_f32_16x16x32_bf16 v[122:125], v[176:179], v[190:193], v[122:125]
	v_mfma_f32_16x16x32_bf16 v[110:113], v[134:137], v[198:201], v[110:113]
	v_mfma_f32_16x16x32_bf16 v[106:109], v[176:179], v[198:201], v[106:109]
	v_mfma_f32_16x16x32_bf16 v[94:97], v[134:137], v[206:209], v[94:97]
	v_mfma_f32_16x16x32_bf16 v[90:93], v[176:179], v[206:209], v[90:93]
	v_mfma_f32_16x16x32_bf16 v[78:81], v[134:137], v[230:233], v[78:81]
	v_mfma_f32_16x16x32_bf16 v[74:77], v[176:179], v[230:233], v[74:77]
	v_mfma_f32_16x16x32_bf16 v[118:121], v[234:237], v[186:189], v[118:121]
	v_mfma_f32_16x16x32_bf16 v[114:117], v[242:245], v[186:189], v[114:117]
	v_mfma_f32_16x16x32_bf16 v[102:105], v[234:237], v[194:197], v[102:105]
	v_mfma_f32_16x16x32_bf16 v[98:101], v[242:245], v[194:197], v[98:101]
	v_mfma_f32_16x16x32_bf16 v[86:89], v[234:237], v[202:205], v[86:89]
	v_mfma_f32_16x16x32_bf16 v[82:85], v[242:245], v[202:205], v[82:85]
	v_mfma_f32_16x16x32_bf16 v[70:73], v[234:237], v[216:219], v[70:73]
	v_mfma_f32_16x16x32_bf16 v[66:69], v[242:245], v[216:219], v[66:69]
	v_mfma_f32_16x16x32_bf16 v[118:121], v[238:241], v[190:193], v[118:121]
	v_mfma_f32_16x16x32_bf16 v[114:117], v[246:249], v[190:193], v[114:117]
	v_mfma_f32_16x16x32_bf16 v[102:105], v[238:241], v[198:201], v[102:105]
	v_mfma_f32_16x16x32_bf16 v[98:101], v[246:249], v[198:201], v[98:101]
	v_mfma_f32_16x16x32_bf16 v[86:89], v[238:241], v[206:209], v[86:89]
	v_mfma_f32_16x16x32_bf16 v[82:85], v[246:249], v[206:209], v[82:85]
	v_mfma_f32_16x16x32_bf16 v[70:73], v[238:241], v[230:233], v[70:73]
	v_mfma_f32_16x16x32_bf16 v[66:69], v[246:249], v[230:233], v[66:69]
	s_setprio 0
	s_barrier
	ds_read_b128 v[186:189], v185 offset:49152
	ds_read_b128 v[190:193], v185 offset:50176
	ds_read_b128 v[194:197], v185 offset:51200
	ds_read_b128 v[198:201], v185 offset:52224
	ds_read_b128 v[202:205], v185 offset:53248
	ds_read_b128 v[206:209], v185 offset:54272
	ds_read_b128 v[216:219], v185 offset:55296
	ds_read_b128 v[230:233], v185 offset:56320
	s_add_i32 s1, s1, s48
	v_lshl_add_u64 v[160:161], v[160:161], 0, s[12:13]
	s_mov_b32 m0, s1
	s_nop 0
	global_load_lds_dwordx4 v[160:161], off
	v_lshl_add_u64 v[160:161], v[220:221], 0, s[12:13]
	s_add_i32 m0, s1, 0x2000
	s_nop 0
	global_load_lds_dwordx4 v[160:161], off
	s_mov_b32 m0, s55
	v_lshl_add_u64 v[160:161], v[250:251], 0, s[12:13]
	global_load_lds_dwordx4 v[160:161], off
	v_lshl_add_u64 v[160:161], v[168:169], 0, s[12:13]
	s_mov_b32 m0, s56
	s_nop 0
	global_load_lds_dwordx4 v[160:161], off
	s_add_u32 s22, s30, 0x40080
	s_addc_u32 s23, s31, 0
	s_add_i32 s1, s33, s48
	s_mov_b32 m0, s1
	s_nop 0
	global_load_lds_dwordx4 v0, s[22:23]
	s_add_i32 m0, s1, 0x2000
	s_nop 0
	global_load_lds_dwordx4 v138, s[22:23]
	s_waitcnt vmcnt(8)
	s_waitcnt lgkmcnt(0)
	s_barrier
	s_setprio 1
	v_mfma_f32_16x16x32_bf16 v[62:65], v[130:133], v[186:189], v[62:65]
	v_mfma_f32_16x16x32_bf16 v[58:61], v[154:157], v[186:189], v[58:61]
	v_mfma_f32_16x16x32_bf16 v[46:49], v[130:133], v[194:197], v[46:49]
	v_mfma_f32_16x16x32_bf16 v[42:45], v[154:157], v[194:197], v[42:45]
	v_mfma_f32_16x16x32_bf16 v[30:33], v[130:133], v[202:205], v[30:33]
	v_mfma_f32_16x16x32_bf16 v[26:29], v[154:157], v[202:205], v[26:29]
	v_mfma_f32_16x16x32_bf16 v[14:17], v[130:133], v[216:219], v[14:17]
	v_mfma_f32_16x16x32_bf16 v[10:13], v[154:157], v[216:219], v[10:13]
	v_mfma_f32_16x16x32_bf16 v[62:65], v[134:137], v[190:193], v[62:65]
	v_mfma_f32_16x16x32_bf16 v[58:61], v[176:179], v[190:193], v[58:61]
	v_mfma_f32_16x16x32_bf16 v[46:49], v[134:137], v[198:201], v[46:49]
	v_mfma_f32_16x16x32_bf16 v[42:45], v[176:179], v[198:201], v[42:45]
	v_mfma_f32_16x16x32_bf16 v[30:33], v[134:137], v[206:209], v[30:33]
	v_mfma_f32_16x16x32_bf16 v[26:29], v[176:179], v[206:209], v[26:29]
	v_mfma_f32_16x16x32_bf16 v[14:17], v[134:137], v[230:233], v[14:17]
	v_mfma_f32_16x16x32_bf16 v[10:13], v[176:179], v[230:233], v[10:13]
	v_mfma_f32_16x16x32_bf16 v[54:57], v[234:237], v[186:189], v[54:57]
	v_mfma_f32_16x16x32_bf16 v[50:53], v[242:245], v[186:189], v[50:53]
	v_mfma_f32_16x16x32_bf16 v[38:41], v[234:237], v[194:197], v[38:41]
	v_mfma_f32_16x16x32_bf16 v[34:37], v[242:245], v[194:197], v[34:37]
	v_mfma_f32_16x16x32_bf16 v[22:25], v[234:237], v[202:205], v[22:25]
	v_mfma_f32_16x16x32_bf16 v[18:21], v[242:245], v[202:205], v[18:21]
	v_mfma_f32_16x16x32_bf16 v[6:9], v[234:237], v[216:219], v[6:9]
	v_mfma_f32_16x16x32_bf16 v[2:5], v[242:245], v[216:219], v[2:5]
	v_mfma_f32_16x16x32_bf16 v[54:57], v[238:241], v[190:193], v[54:57]
	v_mfma_f32_16x16x32_bf16 v[50:53], v[246:249], v[190:193], v[50:53]
	v_mfma_f32_16x16x32_bf16 v[38:41], v[238:241], v[198:201], v[38:41]
	v_mfma_f32_16x16x32_bf16 v[34:37], v[246:249], v[198:201], v[34:37]
	v_mfma_f32_16x16x32_bf16 v[22:25], v[238:241], v[206:209], v[22:25]
	v_mfma_f32_16x16x32_bf16 v[18:21], v[246:249], v[206:209], v[18:21]
	v_mfma_f32_16x16x32_bf16 v[6:9], v[238:241], v[230:233], v[6:9]
	v_mfma_f32_16x16x32_bf16 v[2:5], v[246:249], v[230:233], v[2:5]
	s_setprio 0
	s_add_i32 s44, s44, 2
	s_add_u32 s28, s28, 0x100
	s_addc_u32 s29, s29, 0
	s_add_u32 s25, s25, 0x100
	s_addc_u32 s34, s34, 0
	s_cmp_gt_u32 s44, 13
	s_barrier
	s_cbranch_scc0 .LBB0_362
	s_cmpk_gt_u32 s4, 0xff
	s_cbranch_scc1 .Lrs_proj1_post
	s_barrier
.Lrs_proj1_post:
	v_and_b32_e32 v209, 48, v212
	v_lshl_add_u32 v209, v159, 6, v209
	v_add_u32_e32 v209, 0x20000, v209
	v_and_b32_e32 v131, 64, v212
	v_xor_b32_e32 v130, 16, v212
	v_add_u32_e32 v131, 64, v131
	v_lshl_add_u32 v190, s16, 8, v159
	v_cmp_lt_i32_e32 vcc, v130, v131
	v_add_u32_e32 v156, s54, v190
	v_or_b32_e32 v134, 16, v156
	v_cndmask_b32_e32 v130, v212, v130, vcc
	v_lshlrev_b32_e32 v191, 2, v130
	v_xor_b32_e32 v130, 32, v212
	v_cmp_lt_i32_e32 vcc, v130, v131
	v_ashrrev_i32_e32 v157, 31, v156
	v_ashrrev_i32_e32 v135, 31, v134
	v_cndmask_b32_e32 v130, v212, v130, vcc
	v_lshlrev_b64 v[136:137], 6, v[156:157]
	v_lshlrev_b64 v[134:135], 6, v[134:135]
	v_lshlrev_b32_e32 v192, 2, v130
	v_lshl_add_u64 v[130:131], v[144:145], 0, v[136:137]
	v_lshl_add_u64 v[160:161], v[144:145], 0, v[134:135]
	ds_read_b128 v[130:133], v209
	v_lshl_or_b32 v154, s0, 8, v183
	ds_read_b128 v[186:189], v209 offset:1024
	v_or_b32_e32 v160, 32, v156
	v_ashrrev_i32_e32 v161, 31, v160
	v_lshlrev_b64 v[178:179], 6, v[160:161]
	v_or_b32_e32 v156, 48, v156
	v_lshl_add_u64 v[160:161], v[144:145], 0, v[178:179]
	v_ashrrev_i32_e32 v157, 31, v156
	ds_read_b128 v[194:197], v209 offset:2048
	v_lshlrev_b64 v[160:161], 6, v[156:157]
	v_lshl_add_u64 v[156:157], v[144:145], 0, v[160:161]
	ds_read_b128 v[198:201], v209 offset:3072
	s_ashr_i32 s0, s0, 2
	s_mul_hi_i32 s1, s0, 0x55555556
	s_lshr_b32 s9, s1, 31
	s_add_i32 s1, s1, s9
	s_mul_i32 s1, s1, 3
	s_sub_i32 s0, s0, s1
	s_cmp_lt_i32 s0, 2
	s_cselect_b64 s[0:1], -1, 0
	s_and_b64 s[28:29], s[6:7], s[0:1]
	v_ashrrev_i32_e32 v155, 31, v154
	s_mov_b64 s[44:45], -1
	v_or_b32_e32 v193, 48, v190
	s_waitcnt lgkmcnt(0)
	v_mov_b32_e32 v156, v131
	v_mov_b32_e32 v157, v132
	v_mov_b32_e32 v131, v133
	v_mov_b32_e32 v132, v187
	v_mov_b32_e32 v133, v188
	v_mov_b32_e32 v187, v189
	v_pk_add_f32 v[130:131], v[156:157], v[130:131]
	v_pk_add_f32 v[132:133], v[132:133], v[186:187]
	v_mov_b32_e32 v157, v130
	v_mov_b32_e32 v156, v132
	v_mov_b32_e32 v130, v133
	v_pk_add_f32 v[130:131], v[156:157], v[130:131]
	ds_bpermute_b32 v133, v191, v131
	ds_bpermute_b32 v132, v191, v130
	v_mov_b32_e32 v157, v200
	s_waitcnt lgkmcnt(0)
	v_pk_add_f32 v[130:131], v[130:131], v[132:133]
	ds_bpermute_b32 v133, v192, v131
	ds_bpermute_b32 v132, v192, v130
	s_waitcnt lgkmcnt(0)
	v_pk_add_f32 v[130:131], v[130:131], v[132:133]
	v_mov_b64_e32 v[132:133], s[60:61]
	v_pk_fma_f32 v[130:131], v[130:131], s[58:59], v[132:133] op_sel_hi:[1,0,0]
	s_nop 0
	v_mul_f32_e32 v156, 0x4b800000, v131
	v_cmp_gt_f32_e64 s[42:43], s39, v131
	v_cmp_gt_f32_e32 vcc, s39, v130
	s_nop 0
	v_cndmask_b32_e64 v131, v131, v156, s[42:43]
	v_rsq_f32_e32 v131, v131
	s_nop 0
	v_mul_f32_e32 v156, 0x45800000, v131
	v_cndmask_b32_e64 v184, v131, v156, s[42:43]
	v_mul_f32_e32 v131, 0x4b800000, v130
	v_cndmask_b32_e32 v130, v130, v131, vcc
	v_rsq_f32_e32 v130, v130
	v_mov_b32_e32 v156, v199
	v_mov_b32_e32 v199, v201
	v_pk_add_f32 v[156:157], v[156:157], v[198:199]
	v_mul_f32_e32 v131, 0x45800000, v130
	v_cndmask_b32_e32 v182, v130, v131, vcc
	v_mov_b32_e32 v130, v195
	v_mov_b32_e32 v131, v196
	v_mov_b32_e32 v195, v197
	v_pk_add_f32 v[130:131], v[130:131], v[194:195]
	v_mov_b32_e32 v176, v156
	v_mov_b32_e32 v177, v130
	v_mov_b32_e32 v130, v157
	v_pk_add_f32 v[130:131], v[176:177], v[130:131]
	ds_bpermute_b32 v157, v191, v131
	ds_bpermute_b32 v156, v191, v130
	v_or_b32_e32 v195, 16, v190
	v_or_b32_e32 v194, 32, v190
	s_waitcnt lgkmcnt(0)
	v_pk_add_f32 v[130:131], v[130:131], v[156:157]
	ds_bpermute_b32 v157, v192, v131
	ds_bpermute_b32 v156, v192, v130
	s_waitcnt lgkmcnt(0)
	v_pk_add_f32 v[130:131], v[130:131], v[156:157]
	s_nop 0
	v_pk_fma_f32 v[130:131], v[130:131], s[58:59], v[132:133] op_sel_hi:[1,0,0]
	v_lshlrev_b64 v[156:157], 1, v[154:155]
	v_mul_f32_e32 v132, 0x4b800000, v131
	v_cmp_gt_f32_e64 s[42:43], s39, v131
	v_cmp_gt_f32_e32 vcc, s39, v130
	s_nop 0
	v_cndmask_b32_e64 v131, v131, v132, s[42:43]
	v_rsq_f32_e32 v131, v131
	s_nop 0
	v_mul_f32_e32 v132, 0x45800000, v131
	v_cndmask_b32_e64 v180, v131, v132, s[42:43]
	v_mul_f32_e32 v131, 0x4b800000, v130
	v_cndmask_b32_e32 v130, v130, v131, vcc
	v_rsq_f32_e32 v130, v130
	s_nop 0
	v_mul_f32_e32 v131, 0x45800000, v130
	v_cndmask_b32_e32 v158, v130, v131, vcc
	s_and_b64 vcc, exec, s[28:29]
	s_cbranch_vccnz .LBB0_365
	v_mov_b64_e32 v[176:177], s[68:69]
	v_mad_i64_i32 v[130:131], s[0:1], v190, s86, v[176:177]
	v_lshl_add_u64 v[186:187], v[130:131], 0, v[156:157]
	v_pk_mul_f32 v[132:133], v[128:129], v[184:185] op_sel_hi:[1,0]
	v_pk_mul_f32 v[130:131], v[126:127], v[184:185] op_sel_hi:[1,0]
	v_pk_mul_f32 v[188:189], v[124:125], v[184:185] op_sel_hi:[1,0]
	v_pk_mul_f32 v[196:197], v[122:123], v[184:185] op_sel_hi:[1,0]
	v_cvt_pk_bf16_f32 v130, v130, v131
	v_cvt_pk_bf16_f32 v131, v132, v133
	v_cvt_pk_bf16_f32 v132, v196, v197
	v_cvt_pk_bf16_f32 v133, v188, v189
	global_store_dwordx4 v[186:187], v[130:133], off
	v_pk_mul_f32 v[188:189], v[116:117], v[184:185] op_sel_hi:[1,0]
	v_pk_mul_f32 v[196:197], v[114:115], v[184:185] op_sel_hi:[1,0]
	v_pk_mul_f32 v[132:133], v[120:121], v[184:185] op_sel_hi:[1,0]
	v_pk_mul_f32 v[130:131], v[118:119], v[184:185] op_sel_hi:[1,0]
	s_mov_b64 s[44:45], 0
	v_cvt_pk_bf16_f32 v130, v130, v131
	v_cvt_pk_bf16_f32 v131, v132, v133
	v_cvt_pk_bf16_f32 v132, v196, v197
	v_cvt_pk_bf16_f32 v133, v188, v189
	global_store_dwordx4 v[186:187], v[130:133], off offset:256
	v_pk_mul_f32 v[188:189], v[108:109], v[182:183] op_sel_hi:[1,0]
	v_pk_mul_f32 v[196:197], v[106:107], v[182:183] op_sel_hi:[1,0]
	v_mad_i64_i32 v[130:131], s[0:1], v195, s86, v[176:177]
	v_lshl_add_u64 v[186:187], v[130:131], 0, v[156:157]
	v_pk_mul_f32 v[132:133], v[112:113], v[182:183] op_sel_hi:[1,0]
	v_pk_mul_f32 v[130:131], v[110:111], v[182:183] op_sel_hi:[1,0]
	s_nop 0
	v_cvt_pk_bf16_f32 v130, v130, v131
	v_cvt_pk_bf16_f32 v131, v132, v133
	v_cvt_pk_bf16_f32 v132, v196, v197
	v_cvt_pk_bf16_f32 v133, v188, v189
	global_store_dwordx4 v[186:187], v[130:133], off
	v_pk_mul_f32 v[188:189], v[100:101], v[182:183] op_sel_hi:[1,0]
	v_pk_mul_f32 v[196:197], v[98:99], v[182:183] op_sel_hi:[1,0]
	v_pk_mul_f32 v[132:133], v[104:105], v[182:183] op_sel_hi:[1,0]
	v_pk_mul_f32 v[130:131], v[102:103], v[182:183] op_sel_hi:[1,0]
	s_nop 0
	v_cvt_pk_bf16_f32 v130, v130, v131
	v_cvt_pk_bf16_f32 v131, v132, v133
	v_cvt_pk_bf16_f32 v132, v196, v197
	v_cvt_pk_bf16_f32 v133, v188, v189
	global_store_dwordx4 v[186:187], v[130:133], off offset:256
	v_pk_mul_f32 v[188:189], v[92:93], v[180:181] op_sel_hi:[1,0]
	v_pk_mul_f32 v[196:197], v[90:91], v[180:181] op_sel_hi:[1,0]
	v_mad_i64_i32 v[130:131], s[0:1], v194, s86, v[176:177]
	v_lshl_add_u64 v[186:187], v[130:131], 0, v[156:157]
	v_pk_mul_f32 v[132:133], v[96:97], v[180:181] op_sel_hi:[1,0]
	v_pk_mul_f32 v[130:131], v[94:95], v[180:181] op_sel_hi:[1,0]
	s_nop 0
	v_cvt_pk_bf16_f32 v130, v130, v131
	v_cvt_pk_bf16_f32 v131, v132, v133
	v_cvt_pk_bf16_f32 v132, v196, v197
	v_cvt_pk_bf16_f32 v133, v188, v189
	global_store_dwordx4 v[186:187], v[130:133], off
	v_pk_mul_f32 v[188:189], v[84:85], v[180:181] op_sel_hi:[1,0]
	v_pk_mul_f32 v[196:197], v[82:83], v[180:181] op_sel_hi:[1,0]
	v_pk_mul_f32 v[132:133], v[88:89], v[180:181] op_sel_hi:[1,0]
	v_pk_mul_f32 v[130:131], v[86:87], v[180:181] op_sel_hi:[1,0]
	s_nop 0
	v_cvt_pk_bf16_f32 v130, v130, v131
	v_cvt_pk_bf16_f32 v131, v132, v133
	v_cvt_pk_bf16_f32 v132, v196, v197
	v_cvt_pk_bf16_f32 v133, v188, v189
	global_store_dwordx4 v[186:187], v[130:133], off offset:256
	v_pk_mul_f32 v[186:187], v[76:77], v[158:159] op_sel_hi:[1,0]
	v_pk_mul_f32 v[196:197], v[74:75], v[158:159] op_sel_hi:[1,0]
	v_mad_i64_i32 v[130:131], s[0:1], v193, s86, v[176:177]
	v_lshl_add_u64 v[176:177], v[130:131], 0, v[156:157]
	v_pk_mul_f32 v[132:133], v[80:81], v[158:159] op_sel_hi:[1,0]
	v_pk_mul_f32 v[130:131], v[78:79], v[158:159] op_sel_hi:[1,0]
	v_mad_i64_i32 v[188:189], s[0:1], v193, s86, 0
	v_cvt_pk_bf16_f32 v130, v130, v131
	v_cvt_pk_bf16_f32 v131, v132, v133
	v_cvt_pk_bf16_f32 v132, v196, v197
	v_cvt_pk_bf16_f32 v133, v186, v187
	global_store_dwordx4 v[176:177], v[130:133], off
	v_pk_mul_f32 v[176:177], v[66:67], v[158:159] op_sel_hi:[1,0]
	v_pk_mul_f32 v[186:187], v[68:69], v[158:159] op_sel_hi:[1,0]
	v_pk_mul_f32 v[132:133], v[72:73], v[158:159] op_sel_hi:[1,0]
	v_pk_mul_f32 v[130:131], v[70:71], v[158:159] op_sel_hi:[1,0]
	s_nop 0
	v_cvt_pk_bf16_f32 v130, v130, v131
	v_cvt_pk_bf16_f32 v131, v132, v133
	v_cvt_pk_bf16_f32 v132, v176, v177

.LBB0_367:
	v_add_u32_e32 v83, 0x80, v190
	v_add_u32_e32 v74, s54, v83
	v_or_b32_e32 v70, 16, v74
	v_lshl_add_u64 v[66:67], s[68:69], 0, v[188:189]
	v_ashrrev_i32_e32 v75, 31, v74
	v_ashrrev_i32_e32 v71, 31, v70
	v_lshl_add_u64 v[66:67], v[154:155], 1, v[66:67]
	v_cvt_pk_bf16_f32 v133, v186, v187
	v_lshlrev_b64 v[72:73], 6, v[74:75]
	v_lshlrev_b64 v[70:71], 6, v[70:71]
	global_store_dwordx4 v[66:67], v[130:133], off offset:256
	v_lshl_add_u64 v[66:67], v[144:145], 0, v[72:73]
	v_lshl_add_u64 v[76:77], v[144:145], 0, v[70:71]
	v_and_b32_e32 v209, 48, v212
	v_lshl_add_u32 v209, v159, 6, v209
	v_add_u32_e32 v209, 0x20000, v209
	ds_read_b128 v[66:69], v209 offset:8192
	s_xor_b64 s[28:29], s[28:29], -1
	ds_read_b128 v[84:87], v209 offset:9216
	v_or_b32_e32 v76, 32, v74
	v_ashrrev_i32_e32 v77, 31, v76
	v_lshlrev_b64 v[80:81], 6, v[76:77]
	v_or_b32_e32 v74, 48, v74
	v_lshl_add_u64 v[76:77], v[144:145], 0, v[80:81]
	v_ashrrev_i32_e32 v75, 31, v74
	ds_read_b128 v[88:91], v209 offset:10240
	v_lshlrev_b64 v[76:77], 6, v[74:75]
	v_lshl_add_u64 v[74:75], v[144:145], 0, v[76:77]
	ds_read_b128 v[92:95], v209 offset:11264
	s_mov_b64 s[30:31], -1
	s_waitcnt lgkmcnt(3)
	v_mov_b32_e32 v74, v67
	v_mov_b32_e32 v75, v68
	v_mov_b32_e32 v67, v69
	s_waitcnt lgkmcnt(2)
	v_mov_b32_e32 v68, v85
	v_mov_b32_e32 v69, v86
	v_mov_b32_e32 v85, v87
	v_pk_add_f32 v[66:67], v[74:75], v[66:67]
	v_pk_add_f32 v[68:69], v[68:69], v[84:85]
	v_mov_b32_e32 v75, v66
	v_mov_b32_e32 v74, v68
	v_mov_b32_e32 v66, v69
	v_pk_add_f32 v[66:67], v[74:75], v[66:67]
	ds_bpermute_b32 v69, v191, v67
	ds_bpermute_b32 v68, v191, v66
	s_waitcnt lgkmcnt(2)
	v_mov_b32_e32 v75, v94
	v_add_u32_e32 v87, 0x90, v190
	s_waitcnt lgkmcnt(0)
	v_pk_add_f32 v[66:67], v[66:67], v[68:69]
	ds_bpermute_b32 v69, v192, v67
	ds_bpermute_b32 v68, v192, v66
	s_waitcnt lgkmcnt(0)
	v_pk_add_f32 v[66:67], v[66:67], v[68:69]
	v_mov_b64_e32 v[68:69], s[60:61]
	v_pk_fma_f32 v[66:67], v[66:67], s[58:59], v[68:69] op_sel_hi:[1,0,0]
	s_nop 0
	v_mul_f32_e32 v74, 0x4b800000, v67
	v_cmp_gt_f32_e64 s[42:43], s39, v67
	v_cmp_gt_f32_e32 vcc, s39, v66
	s_nop 0
	v_cndmask_b32_e64 v67, v67, v74, s[42:43]
	v_rsq_f32_e32 v67, v67
	s_nop 0
	v_mul_f32_e32 v74, 0x45800000, v67
	v_cndmask_b32_e64 v86, v67, v74, s[42:43]
	v_mul_f32_e32 v67, 0x4b800000, v66
	v_cndmask_b32_e32 v66, v66, v67, vcc
	v_rsq_f32_e32 v66, v66
	v_mov_b32_e32 v74, v93
	v_mov_b32_e32 v93, v95
	v_pk_add_f32 v[74:75], v[74:75], v[92:93]
	v_mul_f32_e32 v67, 0x45800000, v66
	v_cndmask_b32_e32 v82, v66, v67, vcc
	v_mov_b32_e32 v66, v89
	v_mov_b32_e32 v67, v90
	v_mov_b32_e32 v89, v91
	v_pk_add_f32 v[66:67], v[66:67], v[88:89]
	v_mov_b32_e32 v78, v74
	v_mov_b32_e32 v79, v66
	v_mov_b32_e32 v66, v75
	v_pk_add_f32 v[66:67], v[78:79], v[66:67]
	ds_bpermute_b32 v75, v191, v67
	ds_bpermute_b32 v74, v191, v66
	v_add_u32_e32 v79, 0xa0, v190
	s_waitcnt lgkmcnt(0)
	v_pk_add_f32 v[66:67], v[66:67], v[74:75]
	ds_bpermute_b32 v75, v192, v67
	ds_bpermute_b32 v74, v192, v66
	s_waitcnt lgkmcnt(0)
	v_pk_add_f32 v[66:67], v[66:67], v[74:75]
	s_nop 0
	v_pk_fma_f32 v[66:67], v[66:67], s[58:59], v[68:69] op_sel_hi:[1,0,0]
	v_add_u32_e32 v75, 0xb0, v190
	v_mul_f32_e32 v68, 0x4b800000, v67
	v_cmp_gt_f32_e64 s[42:43], s39, v67
	v_cmp_gt_f32_e32 vcc, s39, v66
	s_nop 0
	v_cndmask_b32_e64 v67, v67, v68, s[42:43]
	v_rsq_f32_e32 v67, v67
	s_nop 0
	v_mul_f32_e32 v68, 0x45800000, v67
	v_cndmask_b32_e64 v78, v67, v68, s[42:43]
	v_mul_f32_e32 v67, 0x4b800000, v66
	v_cndmask_b32_e32 v66, v66, v67, vcc
	v_rsq_f32_e32 v66, v66
	s_nop 0
	v_mul_f32_e32 v67, 0x45800000, v66
	v_cndmask_b32_e32 v74, v66, v67, vcc
	s_andn2_b64 vcc, exec, s[28:29]
	s_cbranch_vccnz .LBB0_369
	v_mov_b64_e32 v[84:85], s[68:69]
	v_mad_i64_i32 v[66:67], s[0:1], v83, s86, v[84:85]
	v_lshl_add_u64 v[88:89], v[66:67], 0, v[156:157]
	v_pk_mul_f32 v[68:69], v[64:65], v[86:87] op_sel_hi:[1,0]
	v_pk_mul_f32 v[66:67], v[62:63], v[86:87] op_sel_hi:[1,0]
	v_pk_mul_f32 v[90:91], v[60:61], v[86:87] op_sel_hi:[1,0]
	v_pk_mul_f32 v[92:93], v[58:59], v[86:87] op_sel_hi:[1,0]
	v_cvt_pk_bf16_f32 v66, v66, v67
	v_cvt_pk_bf16_f32 v67, v68, v69
	v_cvt_pk_bf16_f32 v68, v92, v93
	v_cvt_pk_bf16_f32 v69, v90, v91
	global_store_dwordx4 v[88:89], v[66:69], off
	v_pk_mul_f32 v[90:91], v[52:53], v[86:87] op_sel_hi:[1,0]
	v_pk_mul_f32 v[92:93], v[50:51], v[86:87] op_sel_hi:[1,0]
	v_pk_mul_f32 v[68:69], v[56:57], v[86:87] op_sel_hi:[1,0]
	v_pk_mul_f32 v[66:67], v[54:55], v[86:87] op_sel_hi:[1,0]
	s_mov_b64 s[30:31], 0
	v_cvt_pk_bf16_f32 v66, v66, v67
	v_cvt_pk_bf16_f32 v67, v68, v69
	v_cvt_pk_bf16_f32 v68, v92, v93
	v_cvt_pk_bf16_f32 v69, v90, v91
	global_store_dwordx4 v[88:89], v[66:69], off offset:256
	v_pk_mul_f32 v[90:91], v[44:45], v[82:83] op_sel_hi:[1,0]
	v_pk_mul_f32 v[92:93], v[42:43], v[82:83] op_sel_hi:[1,0]
	v_mad_i64_i32 v[66:67], s[0:1], v87, s86, v[84:85]
	v_lshl_add_u64 v[88:89], v[66:67], 0, v[156:157]
	v_pk_mul_f32 v[68:69], v[48:49], v[82:83] op_sel_hi:[1,0]
	v_pk_mul_f32 v[66:67], v[46:47], v[82:83] op_sel_hi:[1,0]
	s_nop 0
	v_cvt_pk_bf16_f32 v66, v66, v67
	v_cvt_pk_bf16_f32 v67, v68, v69
	v_cvt_pk_bf16_f32 v68, v92, v93
	v_cvt_pk_bf16_f32 v69, v90, v91
	global_store_dwordx4 v[88:89], v[66:69], off
	v_pk_mul_f32 v[90:91], v[36:37], v[82:83] op_sel_hi:[1,0]
	v_pk_mul_f32 v[92:93], v[34:35], v[82:83] op_sel_hi:[1,0]
	v_pk_mul_f32 v[68:69], v[40:41], v[82:83] op_sel_hi:[1,0]
	v_pk_mul_f32 v[66:67], v[38:39], v[82:83] op_sel_hi:[1,0]
	s_nop 0
	v_cvt_pk_bf16_f32 v66, v66, v67
	v_cvt_pk_bf16_f32 v67, v68, v69
	v_cvt_pk_bf16_f32 v68, v92, v93
	v_cvt_pk_bf16_f32 v69, v90, v91
	global_store_dwordx4 v[88:89], v[66:69], off offset:256
	v_pk_mul_f32 v[90:91], v[28:29], v[78:79] op_sel_hi:[1,0]
	v_pk_mul_f32 v[92:93], v[26:27], v[78:79] op_sel_hi:[1,0]
	v_mad_i64_i32 v[66:67], s[0:1], v79, s86, v[84:85]
	v_lshl_add_u64 v[88:89], v[66:67], 0, v[156:157]
	v_pk_mul_f32 v[68:69], v[32:33], v[78:79] op_sel_hi:[1,0]
	v_pk_mul_f32 v[66:67], v[30:31], v[78:79] op_sel_hi:[1,0]
	s_nop 0
	v_cvt_pk_bf16_f32 v66, v66, v67
	v_cvt_pk_bf16_f32 v67, v68, v69
	v_cvt_pk_bf16_f32 v68, v92, v93
	v_cvt_pk_bf16_f32 v69, v90, v91
	global_store_dwordx4 v[88:89], v[66:69], off
	v_pk_mul_f32 v[90:91], v[20:21], v[78:79] op_sel_hi:[1,0]
	v_pk_mul_f32 v[92:93], v[18:19], v[78:79] op_sel_hi:[1,0]
	v_pk_mul_f32 v[68:69], v[24:25], v[78:79] op_sel_hi:[1,0]
	v_pk_mul_f32 v[66:67], v[22:23], v[78:79] op_sel_hi:[1,0]
	s_nop 0
	v_cvt_pk_bf16_f32 v66, v66, v67
	v_cvt_pk_bf16_f32 v67, v68, v69
	v_cvt_pk_bf16_f32 v68, v92, v93
	v_cvt_pk_bf16_f32 v69, v90, v91
	global_store_dwordx4 v[88:89], v[66:69], off offset:256
	v_pk_mul_f32 v[90:91], v[12:13], v[74:75] op_sel_hi:[1,0]
	v_pk_mul_f32 v[92:93], v[10:11], v[74:75] op_sel_hi:[1,0]
	v_mad_i64_i32 v[66:67], s[0:1], v75, s86, v[84:85]
	v_lshl_add_u64 v[84:85], v[66:67], 0, v[156:157]
	v_pk_mul_f32 v[68:69], v[16:17], v[74:75] op_sel_hi:[1,0]
	v_pk_mul_f32 v[66:67], v[14:15], v[74:75] op_sel_hi:[1,0]
	v_mad_i64_i32 v[88:89], s[0:1], v75, s86, 0
	v_cvt_pk_bf16_f32 v66, v66, v67
	v_cvt_pk_bf16_f32 v67, v68, v69
	v_cvt_pk_bf16_f32 v68, v92, v93
	v_cvt_pk_bf16_f32 v69, v90, v91
	global_store_dwordx4 v[84:85], v[66:69], off
	v_pk_mul_f32 v[90:91], v[2:3], v[74:75] op_sel_hi:[1,0]
	v_pk_mul_f32 v[84:85], v[4:5], v[74:75] op_sel_hi:[1,0]
	v_pk_mul_f32 v[68:69], v[8:9], v[74:75] op_sel_hi:[1,0]
	v_pk_mul_f32 v[66:67], v[6:7], v[74:75] op_sel_hi:[1,0]
	s_nop 0
	v_cvt_pk_bf16_f32 v66, v66, v67
	v_cvt_pk_bf16_f32 v67, v68, v69
	v_cvt_pk_bf16_f32 v68, v90, v91
